# pq, wo and merge GEMM epilogues transposed through per-wave LDS with full-row coalesced loads/stores
# speedup vs baseline: 1.0428x; 1.0329x over previous
; template <int WM, class AF, class BF>
; DI void gemm512(f32x16 (&acc)[WM][2], AF arow, int a_kstep, BF brow, int b_kstep, int KT, char* smem) {
;     ...
; #pragma unroll 1
;   for (int kt = 0; kt < KT; kt += 2) {
;     GEMM_STEP(A0, B0, A1, B1, ra0, rb0, ra1, rb1, kt + 2)
;     if (kt + 1 < KT) GEMM_STEP(A1, B1, A0, B0, ra1, rb1, ra0, rb0, kt + 3)
;   }
.LBB0_809:
	ds_read_b128 v[178:181], v169
	ds_read_b128 v[182:185], v168 offset:18432
	ds_read_b128 v[186:189], v168 offset:18464
	ds_read_b128 v[190:193], v169 offset:32
	ds_read_b128 v[194:197], v168 offset:23040
	ds_read_b128 v[198:201], v168 offset:23072
	s_add_i32 s23, s22, 2
	s_waitcnt lgkmcnt(4)
	v_mfma_f32_32x32x16_bf16 v[112:127], v[178:181], v[182:185], v[112:127]
	s_cmp_lt_u32 s22, 6
	s_cselect_b64 s[24:25], -1, 0
	s_and_b64 vcc, s[24:25], exec
	s_cselect_b32 s8, s17, 0x1c0
	s_lshl_b64 s[24:25], s[8:9], 1
	s_min_u32 s8, s22, 4
	s_lshl_b32 s8, s8, 7
	s_waitcnt lgkmcnt(1)
	v_mfma_f32_32x32x16_bf16 v[96:111], v[178:181], v[194:197], v[96:111]
	ds_read_b128 v[178:181], v169 offset:4608
	ds_read_b128 v[202:205], v169 offset:4640
	v_lshl_add_u64 v[214:215], v[164:165], 0, s[8:9]
	s_addk_i32 s17, 0x80
	s_mov_b32 s22, s23
	s_waitcnt lgkmcnt(1)
	v_mfma_f32_32x32x16_bf16 v[80:95], v[178:181], v[182:185], v[80:95]
	v_mfma_f32_32x32x16_bf16 v[64:79], v[178:181], v[194:197], v[64:79]
	v_mfma_f32_32x32x16_bf16 v[112:127], v[190:193], v[186:189], v[112:127]
	v_mfma_f32_32x32x16_bf16 v[96:111], v[190:193], v[198:201], v[96:111]
	s_waitcnt lgkmcnt(0)
	v_mfma_f32_32x32x16_bf16 v[80:95], v[202:205], v[186:189], v[80:95]
	ds_read_b128 v[178:181], v169 offset:64
	ds_read_b128 v[182:185], v168 offset:18496
	ds_read_b128 v[186:189], v168 offset:18528
	ds_read_b128 v[190:193], v169 offset:96
	v_mfma_f32_32x32x16_bf16 v[64:79], v[202:205], v[198:201], v[64:79]
	ds_read_b128 v[194:197], v168 offset:23104
	ds_read_b128 v[198:201], v168 offset:23136
	s_waitcnt lgkmcnt(4)
	v_mfma_f32_32x32x16_bf16 v[112:127], v[178:181], v[182:185], v[112:127]
	s_waitcnt lgkmcnt(1)
	v_mfma_f32_32x32x16_bf16 v[96:111], v[178:181], v[194:197], v[96:111]
	ds_read_b128 v[178:181], v169 offset:4672
	ds_read_b128 v[202:205], v169 offset:4704
	s_waitcnt vmcnt(5)
	ds_write_b128 v152, v[128:131] offset:55296
	s_waitcnt vmcnt(3)
	ds_write_b128 v172, v[136:139] offset:55296
	ds_write_b128 v171, v[132:135]
	s_waitcnt vmcnt(2)
	ds_write_b128 v175, v[140:143]
	s_waitcnt vmcnt(1)
	ds_write_b128 v176, v[144:147]
	s_waitcnt vmcnt(0)
	ds_write_b128 v177, v[148:151]
	v_lshl_add_u64 v[128:129], v[154:155], 0, s[24:25]
	v_lshl_add_u64 v[130:131], v[156:157], 0, s[24:25]
	v_lshl_add_u64 v[132:133], v[158:159], 0, s[24:25]
	v_lshl_add_u64 v[134:135], v[160:161], 0, s[24:25]
	s_waitcnt lgkmcnt(7)
	v_mfma_f32_32x32x16_bf16 v[80:95], v[178:181], v[182:185], v[80:95]
	v_lshl_add_u64 v[136:137], v[162:163], 0, s[24:25]
	v_lshl_add_u64 v[138:139], v[164:165], 0, s[24:25]
	v_mfma_f32_32x32x16_bf16 v[64:79], v[178:181], v[194:197], v[64:79]
	global_load_dwordx4 v[178:181], v[128:129], off
	global_load_dwordx4 v[182:185], v[130:131], off
	v_mfma_f32_32x32x16_bf16 v[112:127], v[190:193], v[186:189], v[112:127]
	v_mfma_f32_32x32x16_bf16 v[96:111], v[190:193], v[198:201], v[96:111]
	s_waitcnt lgkmcnt(6)
	v_mfma_f32_32x32x16_bf16 v[80:95], v[202:205], v[186:189], v[80:95]
	global_load_dwordx4 v[186:189], v[132:133], off
	global_load_dwordx4 v[190:193], v[134:135], off
	global_load_dwordx4 v[194:197], v[136:137], off
	global_load_dwordx4 v[206:209], v[138:139], off
	s_waitcnt lgkmcnt(0)
	s_barrier
	ds_read_b128 v[128:131], v169 offset:55296
	ds_read_b128 v[132:135], v170
	ds_read_b128 v[136:139], v170 offset:32
	ds_read_b128 v[140:143], v169 offset:55328
	ds_read_b128 v[144:147], v170 offset:4608
	ds_read_b128 v[148:151], v170 offset:4640
	v_mfma_f32_32x32x16_bf16 v[64:79], v[202:205], v[198:201], v[64:79]
	s_waitcnt lgkmcnt(4)
	v_mfma_f32_32x32x16_bf16 v[112:127], v[128:131], v[132:135], v[112:127]
	s_waitcnt lgkmcnt(1)
	v_mfma_f32_32x32x16_bf16 v[96:111], v[128:131], v[144:147], v[96:111]
	ds_read_b128 v[128:131], v169 offset:59904
	ds_read_b128 v[198:201], v169 offset:59936
	s_waitcnt lgkmcnt(1)
	v_mfma_f32_32x32x16_bf16 v[80:95], v[128:131], v[132:135], v[80:95]
	v_mfma_f32_32x32x16_bf16 v[64:79], v[128:131], v[144:147], v[64:79]
	v_lshl_add_u64 v[144:145], v[162:163], 0, s[8:9]
	v_mfma_f32_32x32x16_bf16 v[112:127], v[140:143], v[136:139], v[112:127]
	v_mfma_f32_32x32x16_bf16 v[96:111], v[140:143], v[148:151], v[96:111]
	s_waitcnt lgkmcnt(0)
	v_mfma_f32_32x32x16_bf16 v[80:95], v[198:201], v[136:139], v[80:95]
	v_mfma_f32_32x32x16_bf16 v[64:79], v[198:201], v[148:151], v[64:79]
	ds_read_b128 v[128:131], v169 offset:55360
	ds_read_b128 v[132:135], v170 offset:64
	ds_read_b128 v[148:151], v170 offset:96
	ds_read_b128 v[136:139], v169 offset:55392
	ds_read_b128 v[140:143], v170 offset:4672
	ds_read_b128 v[198:201], v170 offset:4704
	s_waitcnt lgkmcnt(4)
	v_mfma_f32_32x32x16_bf16 v[112:127], v[128:131], v[132:135], v[112:127]
	s_waitcnt lgkmcnt(1)
	v_mfma_f32_32x32x16_bf16 v[96:111], v[128:131], v[140:143], v[96:111]
	ds_read_b128 v[128:131], v169 offset:59968
	ds_read_b128 v[202:205], v169 offset:60000
	s_waitcnt lgkmcnt(1)
	v_mfma_f32_32x32x16_bf16 v[80:95], v[128:131], v[132:135], v[80:95]
	v_lshl_add_u64 v[132:133], v[156:157], 0, s[8:9]
	v_lshl_add_u64 v[134:135], v[158:159], 0, s[8:9]
	v_mfma_f32_32x32x16_bf16 v[64:79], v[128:131], v[140:143], v[64:79]
	v_lshl_add_u64 v[128:129], v[154:155], 0, s[8:9]
	v_lshl_add_u64 v[140:141], v[160:161], 0, s[8:9]
	v_mfma_f32_32x32x16_bf16 v[112:127], v[136:139], v[148:151], v[112:127]
	v_mfma_f32_32x32x16_bf16 v[96:111], v[136:139], v[198:201], v[96:111]
	global_load_dwordx4 v[128:131], v[128:129], off offset:384
	s_nop 0
	global_load_dwordx4 v[136:139], v[132:133], off offset:384
	s_nop 0
	global_load_dwordx4 v[132:135], v[134:135], off offset:384
	s_nop 0
	global_load_dwordx4 v[140:143], v[140:141], off offset:384
	s_nop 0
	global_load_dwordx4 v[144:147], v[144:145], off offset:384
	s_waitcnt lgkmcnt(0)
	v_mfma_f32_32x32x16_bf16 v[80:95], v[202:205], v[148:151], v[80:95]
	global_load_dwordx4 v[148:151], v[214:215], off offset:384
	s_waitcnt vmcnt(11)
	ds_write_b128 v152, v[178:181]
	s_waitcnt vmcnt(10)
	ds_write_b128 v172, v[182:185]
	s_waitcnt vmcnt(9)
	ds_write_b128 v152, v[186:189] offset:18432
	s_waitcnt vmcnt(8)
	ds_write_b128 v172, v[190:193] offset:18432
	s_waitcnt vmcnt(7)
	ds_write_b128 v173, v[194:197] offset:18432
	s_waitcnt vmcnt(6)
	ds_write_b128 v174, v[206:209] offset:18432
	s_waitcnt lgkmcnt(0)
	s_barrier
; DI float bflo(unsigned u) { return __uint_as_float(u << 16); }
; DI float bfhi(unsigned u) { return __uint_as_float(u & 0xffff0000u); }
; DI void phase_merge(const Params& p, char* smem) {
;     ...
;   for (int kk = 0;; ++kk) {
;     int mt, nt;
;     if (!xcd_tile(kk, 8, 8, mt, nt)) break;
;     const int m0 = mt * 256, n0 = nt * 128;
;     f32x16 ya[2][2], yb[2][2];
;     zero_acc<2>(ya);
;     zero_acc<2>(yb);
;     gemm512<2>(ya, [&](int r) { return WA + (size_t)(n0 + r) * 512; }, 64, [&](int r) { return ONSA + (size_t)(m0 + r) * 512; }, 64, 8, smem);
;     gemm512<2>(yb, [&](int r) { return WB + (size_t)(n0 + r) * 512; }, 64, [&](int r) { return CACT + (size_t)(m0 + r) * 512; }, 64, 8, smem);
; #pragma unroll
;     for (int i = 0; i < 2; ++i)
; #pragma unroll
;       for (int j = 0; j < 2; ++j)
; #pragma unroll
;         for (int q4 = 0; q4 < 4; ++q4) {
;           const int f = n0 + wm * 64 + i * 32 + q4 * 8 + hh * 4;
;           const size_t t = m0 + wn * 64 + j * 32 + lr;
;           const uint2 ga = *(const uint2*)(MG + t * 2048 + f);
;           const uint2 gb = *(const uint2*)(MG + t * 2048 + 1024 + f);
;           uint2 o;
;           o.x = pack2(bflo(ga.x) * ya[i][j][q4 * 4 + 0] + bflo(gb.x) * yb[i][j][q4 * 4 + 0],
;                       bfhi(ga.x) * ya[i][j][q4 * 4 + 1] + bfhi(gb.x) * yb[i][j][q4 * 4 + 1]);
;           o.y = pack2(bflo(ga.y) * ya[i][j][q4 * 4 + 2] + bflo(gb.y) * yb[i][j][q4 * 4 + 2],
;                       bfhi(ga.y) * ya[i][j][q4 * 4 + 3] + bfhi(gb.y) * yb[i][j][q4 * 4 + 3]);
;           *(uint2*)(MERGED + t * 1024 + f) = o;
;         }
	v_mfma_f32_32x32x16_bf16 v[64:79], v[202:205], v[198:201], v[64:79]
	s_cbranch_vccnz .LBB0_809
	s_waitcnt vmcnt(0)
	s_mov_b32 s22, s15
	s_mov_b32 s24, s16
	s_add_i32 s14, s14, 1
	s_mul_i32 s8, s14, s51
	s_add_i32 s8, s8, s50
	v_mbcnt_lo_u32_b32 v236, -1, 0
	v_mbcnt_hi_u32_b32 v236, -1, v236
	v_lshrrev_b32_e32 v237, 6, v211
	v_and_b32_e32 v238, 31, v236
	v_lshrrev_b32_e32 v239, 5, v236
	v_and_b32_e32 v240, 3, v237
	v_lshrrev_b32_e32 v241, 2, v237
	v_and_b32_e32 v242, 7, v236
	v_lshrrev_b32_e32 v243, 3, v236
	v_lshl_add_u32 v244, v240, 6, v243
	v_add_u32_e32 v244, s22, v244
	v_lshlrev_b32_e32 v245, 6, v241
	v_lshl_add_u32 v245, v242, 3, v245
	v_add_u32_e32 v245, s24, v245
	v_lshlrev_b32_e32 v246, 12, v244
	v_lshl_add_u32 v246, v245, 1, v246
	v_lshlrev_b32_e32 v247, 11, v244
	v_lshl_add_u32 v247, v245, 1, v247
	global_load_dwordx4 v[128:131], v246, s[20:21]
	global_load_dwordx4 v[132:135], v246, s[20:21] offset:2048
	v_add_u32_e32 v246, 0x8000, v246
	global_load_dwordx4 v[136:139], v246, s[20:21]
	global_load_dwordx4 v[140:143], v246, s[20:21] offset:2048
	v_add_u32_e32 v246, 0x8000, v246
	global_load_dwordx4 v[144:147], v246, s[20:21]
	global_load_dwordx4 v[148:151], v246, s[20:21] offset:2048
	v_add_u32_e32 v246, 0x8000, v246
	global_load_dwordx4 v[156:159], v246, s[20:21]
	global_load_dwordx4 v[160:163], v246, s[20:21] offset:2048
	v_add_u32_e32 v246, 0x8000, v246
	global_load_dwordx4 v[168:171], v246, s[20:21]
	global_load_dwordx4 v[172:175], v246, s[20:21] offset:2048
	v_add_u32_e32 v246, 0x8000, v246
	global_load_dwordx4 v[176:179], v246, s[20:21]
	global_load_dwordx4 v[180:183], v246, s[20:21] offset:2048
	v_add_u32_e32 v246, 0x8000, v246
	global_load_dwordx4 v[184:187], v246, s[20:21]
	global_load_dwordx4 v[188:191], v246, s[20:21] offset:2048
	v_add_u32_e32 v246, 0x8000, v246
	global_load_dwordx4 v[192:195], v246, s[20:21]
	global_load_dwordx4 v[196:199], v246, s[20:21] offset:2048
	v_add_u32_e32 v246, 0x8000, v246
	s_barrier
	v_mul_u32_u24_e32 v248, 17408, v237
	v_mul_u32_u24_e32 v249, 272, v238
	v_lshl_add_u32 v249, v239, 4, v249
	v_add3_u32 v249, v249, v248, 64
	v_mul_u32_u24_e32 v250, 272, v243
	v_lshl_add_u32 v250, v242, 5, v250
	v_add3_u32 v250, v250, v248, 64
	ds_write_b128 v249, v[48:51] offset:0
	ds_write_b128 v249, v[112:115] offset:8704
	ds_write_b128 v249, v[52:55] offset:32
	ds_write_b128 v249, v[116:119] offset:8736
	ds_write_b128 v249, v[56:59] offset:64
	ds_write_b128 v249, v[120:123] offset:8768
	ds_write_b128 v249, v[60:63] offset:96
	ds_write_b128 v249, v[124:127] offset:8800
	ds_write_b128 v249, v[16:19] offset:128
	ds_write_b128 v249, v[80:83] offset:8832
	ds_write_b128 v249, v[20:23] offset:160
	ds_write_b128 v249, v[84:87] offset:8864
	ds_write_b128 v249, v[24:27] offset:192
	ds_write_b128 v249, v[88:91] offset:8896
	ds_write_b128 v249, v[28:31] offset:224
	ds_write_b128 v249, v[92:95] offset:8928
	ds_read_b128 v[216:219], v250 offset:0
	ds_read_b128 v[220:223], v250 offset:16
	ds_read_b128 v[224:227], v250 offset:8704
	ds_read_b128 v[228:231], v250 offset:8720
	s_waitcnt vmcnt(14) lgkmcnt(0)
	v_lshlrev_b32_e32 v232, 16, v128
	v_and_b32_e32 v233, 0xffff0000, v128
	v_lshlrev_b32_e32 v234, 16, v132
	v_and_b32_e32 v235, 0xffff0000, v132
	v_pk_mul_f32 v[234:235], v[234:235], v[224:225]
	v_pk_fma_f32 v[232:233], v[232:233], v[216:217], v[234:235]
	v_cvt_pk_bf16_f32 v236, v232, v233
	v_lshlrev_b32_e32 v232, 16, v129
	v_and_b32_e32 v233, 0xffff0000, v129
	v_lshlrev_b32_e32 v234, 16, v133
	v_and_b32_e32 v235, 0xffff0000, v133
	v_pk_mul_f32 v[234:235], v[234:235], v[226:227]
	v_pk_fma_f32 v[232:233], v[232:233], v[218:219], v[234:235]
	v_cvt_pk_bf16_f32 v237, v232, v233
	v_lshlrev_b32_e32 v232, 16, v130
	v_and_b32_e32 v233, 0xffff0000, v130
	v_lshlrev_b32_e32 v234, 16, v134
	v_and_b32_e32 v235, 0xffff0000, v134
	v_pk_mul_f32 v[234:235], v[234:235], v[228:229]
	v_pk_fma_f32 v[232:233], v[232:233], v[220:221], v[234:235]
	v_cvt_pk_bf16_f32 v238, v232, v233
	v_lshlrev_b32_e32 v232, 16, v131
	v_and_b32_e32 v233, 0xffff0000, v131
	v_lshlrev_b32_e32 v234, 16, v135
	v_and_b32_e32 v235, 0xffff0000, v135
	v_pk_mul_f32 v[234:235], v[234:235], v[230:231]
	v_pk_fma_f32 v[232:233], v[232:233], v[222:223], v[234:235]
	v_cvt_pk_bf16_f32 v239, v232, v233
	s_nop 0
	global_store_dwordx4 v247, v[236:239], s[18:19]
	v_add_u32_e32 v247, 0x4000, v247
	ds_read_b128 v[216:219], v250 offset:2176
	ds_read_b128 v[220:223], v250 offset:2192
	ds_read_b128 v[224:227], v250 offset:10880
	ds_read_b128 v[228:231], v250 offset:10896
	s_waitcnt vmcnt(13) lgkmcnt(0)
	v_lshlrev_b32_e32 v232, 16, v136
	v_and_b32_e32 v233, 0xffff0000, v136
	v_lshlrev_b32_e32 v234, 16, v140
	v_and_b32_e32 v235, 0xffff0000, v140
	v_pk_mul_f32 v[234:235], v[234:235], v[224:225]
	v_pk_fma_f32 v[232:233], v[232:233], v[216:217], v[234:235]
	v_cvt_pk_bf16_f32 v236, v232, v233
	v_lshlrev_b32_e32 v232, 16, v137
	v_and_b32_e32 v233, 0xffff0000, v137
	v_lshlrev_b32_e32 v234, 16, v141
	v_and_b32_e32 v235, 0xffff0000, v141
	v_pk_mul_f32 v[234:235], v[234:235], v[226:227]
	v_pk_fma_f32 v[232:233], v[232:233], v[218:219], v[234:235]
	v_cvt_pk_bf16_f32 v237, v232, v233
	v_lshlrev_b32_e32 v232, 16, v138
	v_and_b32_e32 v233, 0xffff0000, v138
	v_lshlrev_b32_e32 v234, 16, v142
	v_and_b32_e32 v235, 0xffff0000, v142
	v_pk_mul_f32 v[234:235], v[234:235], v[228:229]
	v_pk_fma_f32 v[232:233], v[232:233], v[220:221], v[234:235]
	v_cvt_pk_bf16_f32 v238, v232, v233
	v_lshlrev_b32_e32 v232, 16, v139
	v_and_b32_e32 v233, 0xffff0000, v139
	v_lshlrev_b32_e32 v234, 16, v143
	v_and_b32_e32 v235, 0xffff0000, v143
	v_pk_mul_f32 v[234:235], v[234:235], v[230:231]
	v_pk_fma_f32 v[232:233], v[232:233], v[222:223], v[234:235]
	v_cvt_pk_bf16_f32 v239, v232, v233
	s_nop 0
	global_store_dwordx4 v247, v[236:239], s[18:19]
	v_add_u32_e32 v247, 0x4000, v247
	ds_read_b128 v[216:219], v250 offset:4352
	ds_read_b128 v[220:223], v250 offset:4368
	ds_read_b128 v[224:227], v250 offset:13056
	ds_read_b128 v[228:231], v250 offset:13072
	s_waitcnt vmcnt(12) lgkmcnt(0)
; DI float bflo(unsigned u) { return __uint_as_float(u << 16); }
; DI float bfhi(unsigned u) { return __uint_as_float(u & 0xffff0000u); }
; DI void phase_merge(const Params& p, char* smem) {
;     ...
; #pragma unroll
;     for (int i = 0; i < 2; ++i)
; #pragma unroll
;       for (int j = 0; j < 2; ++j)
; #pragma unroll
;         for (int q4 = 0; q4 < 4; ++q4) {
;           const int f = n0 + wm * 64 + i * 32 + q4 * 8 + hh * 4;
;           const size_t t = m0 + wn * 64 + j * 32 + lr;
;           const uint2 ga = *(const uint2*)(MG + t * 2048 + f);
;           const uint2 gb = *(const uint2*)(MG + t * 2048 + 1024 + f);
;           uint2 o;
;           o.x = pack2(bflo(ga.x) * ya[i][j][q4 * 4 + 0] + bflo(gb.x) * yb[i][j][q4 * 4 + 0],
;                       bfhi(ga.x) * ya[i][j][q4 * 4 + 1] + bfhi(gb.x) * yb[i][j][q4 * 4 + 1]);
;           o.y = pack2(bflo(ga.y) * ya[i][j][q4 * 4 + 2] + bflo(gb.y) * yb[i][j][q4 * 4 + 2],
;                       bfhi(ga.y) * ya[i][j][q4 * 4 + 3] + bfhi(gb.y) * yb[i][j][q4 * 4 + 3]);
;           *(uint2*)(MERGED + t * 1024 + f) = o;
;         }
	v_lshlrev_b32_e32 v232, 16, v144
	v_and_b32_e32 v233, 0xffff0000, v144
	v_lshlrev_b32_e32 v234, 16, v148
	v_and_b32_e32 v235, 0xffff0000, v148
	v_pk_mul_f32 v[234:235], v[234:235], v[224:225]
	v_pk_fma_f32 v[232:233], v[232:233], v[216:217], v[234:235]
	v_cvt_pk_bf16_f32 v236, v232, v233
	v_lshlrev_b32_e32 v232, 16, v145
	v_and_b32_e32 v233, 0xffff0000, v145
	v_lshlrev_b32_e32 v234, 16, v149
	v_and_b32_e32 v235, 0xffff0000, v149
	v_pk_mul_f32 v[234:235], v[234:235], v[226:227]
	v_pk_fma_f32 v[232:233], v[232:233], v[218:219], v[234:235]
	v_cvt_pk_bf16_f32 v237, v232, v233
	v_lshlrev_b32_e32 v232, 16, v146
	v_and_b32_e32 v233, 0xffff0000, v146
	v_lshlrev_b32_e32 v234, 16, v150
	v_and_b32_e32 v235, 0xffff0000, v150
	v_pk_mul_f32 v[234:235], v[234:235], v[228:229]
	v_pk_fma_f32 v[232:233], v[232:233], v[220:221], v[234:235]
	v_cvt_pk_bf16_f32 v238, v232, v233
	v_lshlrev_b32_e32 v232, 16, v147
	v_and_b32_e32 v233, 0xffff0000, v147
	v_lshlrev_b32_e32 v234, 16, v151
	v_and_b32_e32 v235, 0xffff0000, v151
	v_pk_mul_f32 v[234:235], v[234:235], v[230:231]
	v_pk_fma_f32 v[232:233], v[232:233], v[222:223], v[234:235]
	v_cvt_pk_bf16_f32 v239, v232, v233
	s_nop 0
	global_store_dwordx4 v247, v[236:239], s[18:19]
	v_add_u32_e32 v247, 0x4000, v247
	ds_read_b128 v[216:219], v250 offset:6528
	ds_read_b128 v[220:223], v250 offset:6544
	ds_read_b128 v[224:227], v250 offset:15232
	ds_read_b128 v[228:231], v250 offset:15248
	s_waitcnt vmcnt(11) lgkmcnt(0)
	v_lshlrev_b32_e32 v232, 16, v156
	v_and_b32_e32 v233, 0xffff0000, v156
	v_lshlrev_b32_e32 v234, 16, v160
	v_and_b32_e32 v235, 0xffff0000, v160
	v_pk_mul_f32 v[234:235], v[234:235], v[224:225]
	v_pk_fma_f32 v[232:233], v[232:233], v[216:217], v[234:235]
	v_cvt_pk_bf16_f32 v236, v232, v233
	v_lshlrev_b32_e32 v232, 16, v157
	v_and_b32_e32 v233, 0xffff0000, v157
	v_lshlrev_b32_e32 v234, 16, v161
	v_and_b32_e32 v235, 0xffff0000, v161
	v_pk_mul_f32 v[234:235], v[234:235], v[226:227]
	v_pk_fma_f32 v[232:233], v[232:233], v[218:219], v[234:235]
	v_cvt_pk_bf16_f32 v237, v232, v233
	v_lshlrev_b32_e32 v232, 16, v158
	v_and_b32_e32 v233, 0xffff0000, v158
	v_lshlrev_b32_e32 v234, 16, v162
	v_and_b32_e32 v235, 0xffff0000, v162
	v_pk_mul_f32 v[234:235], v[234:235], v[228:229]
	v_pk_fma_f32 v[232:233], v[232:233], v[220:221], v[234:235]
	v_cvt_pk_bf16_f32 v238, v232, v233
	v_lshlrev_b32_e32 v232, 16, v159
	v_and_b32_e32 v233, 0xffff0000, v159
	v_lshlrev_b32_e32 v234, 16, v163
	v_and_b32_e32 v235, 0xffff0000, v163
	v_pk_mul_f32 v[234:235], v[234:235], v[230:231]
	v_pk_fma_f32 v[232:233], v[232:233], v[222:223], v[234:235]
	v_cvt_pk_bf16_f32 v239, v232, v233
	s_nop 0
	global_store_dwordx4 v247, v[236:239], s[18:19]
	v_add_u32_e32 v247, 0x4000, v247
	ds_write_b128 v249, v[32:35] offset:0
	ds_write_b128 v249, v[96:99] offset:8704
	ds_write_b128 v249, v[36:39] offset:32
	ds_write_b128 v249, v[100:103] offset:8736
	ds_write_b128 v249, v[40:43] offset:64
	ds_write_b128 v249, v[104:107] offset:8768
	ds_write_b128 v249, v[44:47] offset:96
	ds_write_b128 v249, v[108:111] offset:8800
	ds_write_b128 v249, v[0:3] offset:128
	ds_write_b128 v249, v[64:67] offset:8832
	ds_write_b128 v249, v[4:7] offset:160
	ds_write_b128 v249, v[68:71] offset:8864
	ds_write_b128 v249, v[8:11] offset:192
	ds_write_b128 v249, v[72:75] offset:8896
	ds_write_b128 v249, v[12:15] offset:224
	ds_write_b128 v249, v[76:79] offset:8928
	ds_read_b128 v[216:219], v250 offset:0
	ds_read_b128 v[220:223], v250 offset:16
	ds_read_b128 v[224:227], v250 offset:8704
	ds_read_b128 v[228:231], v250 offset:8720
	s_waitcnt vmcnt(10) lgkmcnt(0)
	v_lshlrev_b32_e32 v232, 16, v168
	v_and_b32_e32 v233, 0xffff0000, v168
	v_lshlrev_b32_e32 v234, 16, v172
	v_and_b32_e32 v235, 0xffff0000, v172
	v_pk_mul_f32 v[234:235], v[234:235], v[224:225]
	v_pk_fma_f32 v[232:233], v[232:233], v[216:217], v[234:235]
	v_cvt_pk_bf16_f32 v236, v232, v233
	v_lshlrev_b32_e32 v232, 16, v169
	v_and_b32_e32 v233, 0xffff0000, v169
	v_lshlrev_b32_e32 v234, 16, v173
	v_and_b32_e32 v235, 0xffff0000, v173
	v_pk_mul_f32 v[234:235], v[234:235], v[226:227]
	v_pk_fma_f32 v[232:233], v[232:233], v[218:219], v[234:235]
	v_cvt_pk_bf16_f32 v237, v232, v233
	v_lshlrev_b32_e32 v232, 16, v170
	v_and_b32_e32 v233, 0xffff0000, v170
	v_lshlrev_b32_e32 v234, 16, v174
	v_and_b32_e32 v235, 0xffff0000, v174
	v_pk_mul_f32 v[234:235], v[234:235], v[228:229]
	v_pk_fma_f32 v[232:233], v[232:233], v[220:221], v[234:235]
	v_cvt_pk_bf16_f32 v238, v232, v233
	v_lshlrev_b32_e32 v232, 16, v171
	v_and_b32_e32 v233, 0xffff0000, v171
	v_lshlrev_b32_e32 v234, 16, v175
	v_and_b32_e32 v235, 0xffff0000, v175
	v_pk_mul_f32 v[234:235], v[234:235], v[230:231]
	v_pk_fma_f32 v[232:233], v[232:233], v[222:223], v[234:235]
	v_cvt_pk_bf16_f32 v239, v232, v233
	s_nop 0
	global_store_dwordx4 v247, v[236:239], s[18:19]
	v_add_u32_e32 v247, 0x4000, v247
	ds_read_b128 v[216:219], v250 offset:2176
	ds_read_b128 v[220:223], v250 offset:2192
	ds_read_b128 v[224:227], v250 offset:10880
	ds_read_b128 v[228:231], v250 offset:10896
	s_waitcnt vmcnt(9) lgkmcnt(0)
; DI float bflo(unsigned u) { return __uint_as_float(u << 16); }
; DI float bfhi(unsigned u) { return __uint_as_float(u & 0xffff0000u); }
; DI void phase_merge(const Params& p, char* smem) {
;     ...
; #pragma unroll
;     for (int i = 0; i < 2; ++i)
; #pragma unroll
;       for (int j = 0; j < 2; ++j)
; #pragma unroll
;         for (int q4 = 0; q4 < 4; ++q4) {
;           const int f = n0 + wm * 64 + i * 32 + q4 * 8 + hh * 4;
;           const size_t t = m0 + wn * 64 + j * 32 + lr;
;           const uint2 ga = *(const uint2*)(MG + t * 2048 + f);
;           const uint2 gb = *(const uint2*)(MG + t * 2048 + 1024 + f);
;           uint2 o;
;           o.x = pack2(bflo(ga.x) * ya[i][j][q4 * 4 + 0] + bflo(gb.x) * yb[i][j][q4 * 4 + 0],
;                       bfhi(ga.x) * ya[i][j][q4 * 4 + 1] + bfhi(gb.x) * yb[i][j][q4 * 4 + 1]);
;           o.y = pack2(bflo(ga.y) * ya[i][j][q4 * 4 + 2] + bflo(gb.y) * yb[i][j][q4 * 4 + 2],
;                       bfhi(ga.y) * ya[i][j][q4 * 4 + 3] + bfhi(gb.y) * yb[i][j][q4 * 4 + 3]);
;           *(uint2*)(MERGED + t * 1024 + f) = o;
;         }
	v_lshlrev_b32_e32 v232, 16, v176
	v_and_b32_e32 v233, 0xffff0000, v176
	v_lshlrev_b32_e32 v234, 16, v180
	v_and_b32_e32 v235, 0xffff0000, v180
	v_pk_mul_f32 v[234:235], v[234:235], v[224:225]
	v_pk_fma_f32 v[232:233], v[232:233], v[216:217], v[234:235]
	v_cvt_pk_bf16_f32 v236, v232, v233
	v_lshlrev_b32_e32 v232, 16, v177
	v_and_b32_e32 v233, 0xffff0000, v177
	v_lshlrev_b32_e32 v234, 16, v181
	v_and_b32_e32 v235, 0xffff0000, v181
	v_pk_mul_f32 v[234:235], v[234:235], v[226:227]
	v_pk_fma_f32 v[232:233], v[232:233], v[218:219], v[234:235]
	v_cvt_pk_bf16_f32 v237, v232, v233
	v_lshlrev_b32_e32 v232, 16, v178
	v_and_b32_e32 v233, 0xffff0000, v178
	v_lshlrev_b32_e32 v234, 16, v182
	v_and_b32_e32 v235, 0xffff0000, v182
	v_pk_mul_f32 v[234:235], v[234:235], v[228:229]
	v_pk_fma_f32 v[232:233], v[232:233], v[220:221], v[234:235]
	v_cvt_pk_bf16_f32 v238, v232, v233
	v_lshlrev_b32_e32 v232, 16, v179
	v_and_b32_e32 v233, 0xffff0000, v179
	v_lshlrev_b32_e32 v234, 16, v183
	v_and_b32_e32 v235, 0xffff0000, v183
	v_pk_mul_f32 v[234:235], v[234:235], v[230:231]
	v_pk_fma_f32 v[232:233], v[232:233], v[222:223], v[234:235]
	v_cvt_pk_bf16_f32 v239, v232, v233
	s_nop 0
	global_store_dwordx4 v247, v[236:239], s[18:19]
	v_add_u32_e32 v247, 0x4000, v247
	ds_read_b128 v[216:219], v250 offset:4352
	ds_read_b128 v[220:223], v250 offset:4368
	ds_read_b128 v[224:227], v250 offset:13056
	ds_read_b128 v[228:231], v250 offset:13072
	s_waitcnt vmcnt(8) lgkmcnt(0)
	v_lshlrev_b32_e32 v232, 16, v184
	v_and_b32_e32 v233, 0xffff0000, v184
	v_lshlrev_b32_e32 v234, 16, v188
	v_and_b32_e32 v235, 0xffff0000, v188
	v_pk_mul_f32 v[234:235], v[234:235], v[224:225]
	v_pk_fma_f32 v[232:233], v[232:233], v[216:217], v[234:235]
	v_cvt_pk_bf16_f32 v236, v232, v233
	v_lshlrev_b32_e32 v232, 16, v185
	v_and_b32_e32 v233, 0xffff0000, v185
	v_lshlrev_b32_e32 v234, 16, v189
	v_and_b32_e32 v235, 0xffff0000, v189
	v_pk_mul_f32 v[234:235], v[234:235], v[226:227]
	v_pk_fma_f32 v[232:233], v[232:233], v[218:219], v[234:235]
	v_cvt_pk_bf16_f32 v237, v232, v233
	v_lshlrev_b32_e32 v232, 16, v186
	v_and_b32_e32 v233, 0xffff0000, v186
	v_lshlrev_b32_e32 v234, 16, v190
	v_and_b32_e32 v235, 0xffff0000, v190
	v_pk_mul_f32 v[234:235], v[234:235], v[228:229]
	v_pk_fma_f32 v[232:233], v[232:233], v[220:221], v[234:235]
	v_cvt_pk_bf16_f32 v238, v232, v233
	v_lshlrev_b32_e32 v232, 16, v187
	v_and_b32_e32 v233, 0xffff0000, v187
	v_lshlrev_b32_e32 v234, 16, v191
	v_and_b32_e32 v235, 0xffff0000, v191
	v_pk_mul_f32 v[234:235], v[234:235], v[230:231]
	v_pk_fma_f32 v[232:233], v[232:233], v[222:223], v[234:235]
	v_cvt_pk_bf16_f32 v239, v232, v233
	s_nop 0
	global_store_dwordx4 v247, v[236:239], s[18:19]
	v_add_u32_e32 v247, 0x4000, v247
	ds_read_b128 v[216:219], v250 offset:6528
	ds_read_b128 v[220:223], v250 offset:6544
	ds_read_b128 v[224:227], v250 offset:15232
	ds_read_b128 v[228:231], v250 offset:15248
	s_waitcnt vmcnt(7) lgkmcnt(0)
	v_lshlrev_b32_e32 v232, 16, v192
	v_and_b32_e32 v233, 0xffff0000, v192
	v_lshlrev_b32_e32 v234, 16, v196
	v_and_b32_e32 v235, 0xffff0000, v196
	v_pk_mul_f32 v[234:235], v[234:235], v[224:225]
	v_pk_fma_f32 v[232:233], v[232:233], v[216:217], v[234:235]
	v_cvt_pk_bf16_f32 v236, v232, v233
	v_lshlrev_b32_e32 v232, 16, v193
	v_and_b32_e32 v233, 0xffff0000, v193
	v_lshlrev_b32_e32 v234, 16, v197
	v_and_b32_e32 v235, 0xffff0000, v197
	v_pk_mul_f32 v[234:235], v[234:235], v[226:227]
	v_pk_fma_f32 v[232:233], v[232:233], v[218:219], v[234:235]
	v_cvt_pk_bf16_f32 v237, v232, v233
	v_lshlrev_b32_e32 v232, 16, v194
	v_and_b32_e32 v233, 0xffff0000, v194
	v_lshlrev_b32_e32 v234, 16, v198
	v_and_b32_e32 v235, 0xffff0000, v198
	v_pk_mul_f32 v[234:235], v[234:235], v[228:229]
	v_pk_fma_f32 v[232:233], v[232:233], v[220:221], v[234:235]
	v_cvt_pk_bf16_f32 v238, v232, v233
	v_lshlrev_b32_e32 v232, 16, v195
	v_and_b32_e32 v233, 0xffff0000, v195
	v_lshlrev_b32_e32 v234, 16, v199
	v_and_b32_e32 v235, 0xffff0000, v199
	v_pk_mul_f32 v[234:235], v[234:235], v[230:231]
	v_pk_fma_f32 v[232:233], v[232:233], v[222:223], v[234:235]
	v_cvt_pk_bf16_f32 v239, v232, v233
	s_nop 0
	global_store_dwordx4 v247, v[236:239], s[18:19]
	v_add_u32_e32 v247, 0x4000, v247
	s_cmp_lt_u32 s8, 64
	s_cbranch_scc1 .LBB0_806

; template <int WM, class AF, class BF>
; DI void gemm512(f32x16 (&acc)[WM][2], AF arow, int a_kstep, BF brow, int b_kstep, int KT, char* smem) {
;     ...
; #pragma unroll 1
;   for (int kt = 0; kt < KT; kt += 2) {
;     GEMM_STEP(A0, B0, A1, B1, ra0, rb0, ra1, rb1, kt + 2)
;     if (kt + 1 < KT) GEMM_STEP(A1, B1, A0, B0, ra1, rb1, ra0, rb0, kt + 3)
;   }
.LBB0_866:
	ds_read_b128 v[160:163], v220
	ds_read_b128 v[164:167], v219 offset:36864
	ds_read_b128 v[168:171], v219 offset:36896
	ds_read_b128 v[172:175], v220 offset:32
	ds_read_b128 v[176:179], v219 offset:41472
	ds_read_b128 v[180:183], v219 offset:41504
	s_add_i32 s16, s15, 2
	s_waitcnt lgkmcnt(4)
	v_mfma_f32_32x32x16_bf16 v[112:127], v[160:163], v[164:167], v[112:127]
	s_cmp_lt_u32 s15, 14
	s_cselect_b64 s[22:23], -1, 0
	s_and_b64 vcc, s[22:23], exec
	s_cselect_b32 s4, s14, 0x3c0
	s_lshl_b64 s[22:23], s[4:5], 1
	s_min_u32 s4, s15, 12
	s_lshl_b32 s4, s4, 7
	s_waitcnt lgkmcnt(1)
	v_mfma_f32_32x32x16_bf16 v[96:111], v[160:163], v[176:179], v[96:111]
	ds_read_b128 v[160:163], v220 offset:4608
	ds_read_b128 v[184:187], v220 offset:4640
	v_lshl_add_u64 v[240:241], v[206:207], 0, s[4:5]
	v_lshl_add_u64 v[242:243], v[208:209], 0, s[4:5]
	s_addk_i32 s14, 0x80
	s_mov_b32 s15, s16
	s_waitcnt lgkmcnt(1)
	v_mfma_f32_32x32x16_bf16 v[80:95], v[160:163], v[164:167], v[80:95]
	v_mfma_f32_32x32x16_bf16 v[64:79], v[160:163], v[176:179], v[64:79]
	ds_read_b128 v[160:163], v220 offset:9216
	ds_read_b128 v[188:191], v220 offset:9248
	s_waitcnt lgkmcnt(1)
	v_mfma_f32_32x32x16_bf16 v[48:63], v[160:163], v[164:167], v[48:63]
	v_mfma_f32_32x32x16_bf16 v[32:47], v[160:163], v[176:179], v[32:47]
	ds_read_b128 v[160:163], v220 offset:13824
	ds_read_b128 v[232:235], v220 offset:13856
	s_waitcnt lgkmcnt(1)
	v_mfma_f32_32x32x16_bf16 v[16:31], v[160:163], v[164:167], v[16:31]
	v_mfma_f32_32x32x16_bf16 v[0:15], v[160:163], v[176:179], v[0:15]
	v_mfma_f32_32x32x16_bf16 v[112:127], v[172:175], v[168:171], v[112:127]
	v_mfma_f32_32x32x16_bf16 v[96:111], v[172:175], v[180:183], v[96:111]
	v_mfma_f32_32x32x16_bf16 v[80:95], v[184:187], v[168:171], v[80:95]
	v_mfma_f32_32x32x16_bf16 v[64:79], v[184:187], v[180:183], v[64:79]
	v_mfma_f32_32x32x16_bf16 v[48:63], v[188:191], v[168:171], v[48:63]
	s_waitcnt lgkmcnt(0)
	v_mfma_f32_32x32x16_bf16 v[16:31], v[232:235], v[168:171], v[16:31]
	ds_read_b128 v[160:163], v220 offset:64
	ds_read_b128 v[164:167], v219 offset:36928
	ds_read_b128 v[176:179], v219 offset:36960
	ds_read_b128 v[168:171], v220 offset:96
	v_mfma_f32_32x32x16_bf16 v[0:15], v[232:235], v[180:183], v[0:15]
	ds_read_b128 v[172:175], v219 offset:41536
	ds_read_b128 v[232:235], v219 offset:41568
	v_mfma_f32_32x32x16_bf16 v[32:47], v[188:191], v[180:183], v[32:47]
	s_waitcnt lgkmcnt(4)
	v_mfma_f32_32x32x16_bf16 v[112:127], v[160:163], v[164:167], v[112:127]
	s_waitcnt lgkmcnt(1)
	v_mfma_f32_32x32x16_bf16 v[96:111], v[160:163], v[172:175], v[96:111]
	ds_read_b128 v[160:163], v220 offset:4672
	ds_read_b128 v[180:183], v220 offset:4704
	s_waitcnt lgkmcnt(1)
	v_mfma_f32_32x32x16_bf16 v[80:95], v[160:163], v[164:167], v[80:95]
	v_mfma_f32_32x32x16_bf16 v[64:79], v[160:163], v[172:175], v[64:79]
	ds_read_b128 v[160:163], v220 offset:9280
	ds_read_b128 v[184:187], v220 offset:9312
	s_waitcnt lgkmcnt(1)
	v_mfma_f32_32x32x16_bf16 v[48:63], v[160:163], v[164:167], v[48:63]
	v_mfma_f32_32x32x16_bf16 v[32:47], v[160:163], v[172:175], v[32:47]
	ds_read_b128 v[160:163], v220 offset:13888
	ds_read_b128 v[236:239], v220 offset:13920
	s_waitcnt vmcnt(7)
	ds_write_b128 v223, v[128:131]
	s_waitcnt vmcnt(5)
	ds_write_b128 v224, v[136:139]
	s_waitcnt vmcnt(4)
	ds_write_b128 v225, v[140:143]
	s_waitcnt vmcnt(3)
	ds_write_b128 v226, v[144:147]
	ds_write_b128 v227, v[132:135]
	s_waitcnt vmcnt(2)
	ds_write_b128 v228, v[148:151]
	s_waitcnt vmcnt(1)
	ds_write_b128 v229, v[152:155]
	s_waitcnt vmcnt(0)
	ds_write_b128 v230, v[156:159]
	v_lshl_add_u64 v[128:129], v[194:195], 0, s[22:23]
	v_lshl_add_u64 v[130:131], v[196:197], 0, s[22:23]
	v_lshl_add_u64 v[132:133], v[198:199], 0, s[22:23]
	v_lshl_add_u64 v[134:135], v[200:201], 0, s[22:23]
	s_waitcnt lgkmcnt(9)
	v_mfma_f32_32x32x16_bf16 v[16:31], v[160:163], v[164:167], v[16:31]
	v_lshl_add_u64 v[136:137], v[202:203], 0, s[22:23]
	v_lshl_add_u64 v[138:139], v[204:205], 0, s[22:23]
	v_lshl_add_u64 v[140:141], v[206:207], 0, s[22:23]
	v_lshl_add_u64 v[142:143], v[208:209], 0, s[22:23]
	v_mfma_f32_32x32x16_bf16 v[112:127], v[168:171], v[176:179], v[112:127]
	v_mfma_f32_32x32x16_bf16 v[96:111], v[168:171], v[232:235], v[96:111]
	v_mfma_f32_32x32x16_bf16 v[0:15], v[160:163], v[172:175], v[0:15]
	global_load_dwordx4 v[160:163], v[128:129], off
	global_load_dwordx4 v[164:167], v[130:131], off
	global_load_dwordx4 v[168:171], v[132:133], off
	global_load_dwordx4 v[172:175], v[134:135], off
	v_mfma_f32_32x32x16_bf16 v[80:95], v[180:183], v[176:179], v[80:95]
	v_mfma_f32_32x32x16_bf16 v[64:79], v[180:183], v[232:235], v[64:79]
	v_mfma_f32_32x32x16_bf16 v[48:63], v[184:187], v[176:179], v[48:63]
	v_mfma_f32_32x32x16_bf16 v[32:47], v[184:187], v[232:235], v[32:47]
	s_waitcnt lgkmcnt(8)
	v_mfma_f32_32x32x16_bf16 v[16:31], v[236:239], v[176:179], v[16:31]
	global_load_dwordx4 v[176:179], v[136:137], off
	global_load_dwordx4 v[180:183], v[138:139], off
	global_load_dwordx4 v[184:187], v[140:141], off
	global_load_dwordx4 v[188:191], v[142:143], off
	s_waitcnt lgkmcnt(0)
	s_barrier
; template <int WM, class AF, class BF>
; DI void gemm512(f32x16 (&acc)[WM][2], AF arow, int a_kstep, BF brow, int b_kstep, int KT, char* smem) {
;     ...
; #pragma unroll 1
;   for (int kt = 0; kt < KT; kt += 2) {
;     GEMM_STEP(A0, B0, A1, B1, ra0, rb0, ra1, rb1, kt + 2)
;     if (kt + 1 < KT) GEMM_STEP(A1, B1, A0, B0, ra1, rb1, ra0, rb0, kt + 3)
;   }
; DI void phase_wo(const Params& p, char* smem) {
;     ...
;   for (int kk = 0;; ++kk) {
;     int mt, nt;
;     if (!xcd_tile(kk, 4, 8, mt, nt)) break;
;     const int m0 = mt * 256, n0 = nt * 256;
;     f32x16 acc[4][2];
;     zero_acc<4>(acc);
;     gemm512<4>(acc, [&](int r) { return WT + (size_t)(n0 + r) * 1024; }, 64, [&](int r) { return MERGED + (size_t)(m0 + r) * 1024; }, 64, 16, smem);
	ds_read_b128 v[128:131], v222
	ds_read_b128 v[132:135], v221
	ds_read_b128 v[136:139], v221 offset:32
	ds_read_b128 v[140:143], v222 offset:32
	ds_read_b128 v[144:147], v221 offset:4608
	ds_read_b128 v[148:151], v221 offset:4640
	s_waitcnt lgkmcnt(4)
	v_mfma_f32_32x32x16_bf16 v[112:127], v[128:131], v[132:135], v[112:127]
	s_waitcnt lgkmcnt(1)
	v_mfma_f32_32x32x16_bf16 v[96:111], v[128:131], v[144:147], v[96:111]
	ds_read_b128 v[128:131], v222 offset:4608
	ds_read_b128 v[152:155], v222 offset:4640
	v_mfma_f32_32x32x16_bf16 v[0:15], v[236:239], v[232:235], v[0:15]
	s_waitcnt lgkmcnt(1)
	v_mfma_f32_32x32x16_bf16 v[80:95], v[128:131], v[132:135], v[80:95]
	v_mfma_f32_32x32x16_bf16 v[64:79], v[128:131], v[144:147], v[64:79]
	ds_read_b128 v[128:131], v222 offset:9216
	ds_read_b128 v[156:159], v222 offset:9248
	s_waitcnt lgkmcnt(1)
	v_mfma_f32_32x32x16_bf16 v[48:63], v[128:131], v[132:135], v[48:63]
	v_mfma_f32_32x32x16_bf16 v[32:47], v[128:131], v[144:147], v[32:47]
	ds_read_b128 v[128:131], v222 offset:13824
	ds_read_b128 v[232:235], v222 offset:13856
	s_waitcnt lgkmcnt(1)
	v_mfma_f32_32x32x16_bf16 v[16:31], v[128:131], v[132:135], v[16:31]
	v_mfma_f32_32x32x16_bf16 v[0:15], v[128:131], v[144:147], v[0:15]
	v_mfma_f32_32x32x16_bf16 v[112:127], v[140:143], v[136:139], v[112:127]
	v_mfma_f32_32x32x16_bf16 v[96:111], v[140:143], v[148:151], v[96:111]
	v_mfma_f32_32x32x16_bf16 v[80:95], v[152:155], v[136:139], v[80:95]
	v_mfma_f32_32x32x16_bf16 v[64:79], v[152:155], v[148:151], v[64:79]
	v_lshl_add_u64 v[152:153], v[202:203], 0, s[4:5]
	v_lshl_add_u64 v[154:155], v[204:205], 0, s[4:5]
	v_mfma_f32_32x32x16_bf16 v[48:63], v[156:159], v[136:139], v[48:63]
	v_mfma_f32_32x32x16_bf16 v[32:47], v[156:159], v[148:151], v[32:47]
	s_waitcnt lgkmcnt(0)
	v_mfma_f32_32x32x16_bf16 v[16:31], v[232:235], v[136:139], v[16:31]
	ds_read_b128 v[128:131], v222 offset:64
	ds_read_b128 v[132:135], v221 offset:64
	ds_read_b128 v[156:159], v221 offset:96
	ds_read_b128 v[136:139], v222 offset:96
	v_mfma_f32_32x32x16_bf16 v[0:15], v[232:235], v[148:151], v[0:15]
	ds_read_b128 v[140:143], v221 offset:4672
	ds_read_b128 v[232:235], v221 offset:4704
	s_waitcnt lgkmcnt(4)
	v_mfma_f32_32x32x16_bf16 v[112:127], v[128:131], v[132:135], v[112:127]
	s_waitcnt lgkmcnt(1)
	v_mfma_f32_32x32x16_bf16 v[96:111], v[128:131], v[140:143], v[96:111]
	ds_read_b128 v[128:131], v222 offset:4672
	ds_read_b128 v[144:147], v222 offset:4704
	s_waitcnt lgkmcnt(1)
	v_mfma_f32_32x32x16_bf16 v[80:95], v[128:131], v[132:135], v[80:95]
	v_mfma_f32_32x32x16_bf16 v[64:79], v[128:131], v[140:143], v[64:79]
	ds_read_b128 v[128:131], v222 offset:9280
	ds_read_b128 v[148:151], v222 offset:9312
	s_waitcnt lgkmcnt(1)
	v_mfma_f32_32x32x16_bf16 v[48:63], v[128:131], v[132:135], v[48:63]
	v_mfma_f32_32x32x16_bf16 v[32:47], v[128:131], v[140:143], v[32:47]
	ds_read_b128 v[128:131], v222 offset:13888
	ds_read_b128 v[236:239], v222 offset:13920
	s_waitcnt lgkmcnt(1)
	v_mfma_f32_32x32x16_bf16 v[16:31], v[128:131], v[132:135], v[16:31]
	v_lshl_add_u64 v[132:133], v[196:197], 0, s[4:5]
	v_lshl_add_u64 v[134:135], v[198:199], 0, s[4:5]
	v_mfma_f32_32x32x16_bf16 v[0:15], v[128:131], v[140:143], v[0:15]
	v_lshl_add_u64 v[128:129], v[194:195], 0, s[4:5]
	v_mfma_f32_32x32x16_bf16 v[80:95], v[144:147], v[156:159], v[80:95]
	v_mfma_f32_32x32x16_bf16 v[64:79], v[144:147], v[232:235], v[64:79]
	v_lshl_add_u64 v[144:145], v[200:201], 0, s[4:5]
	v_mfma_f32_32x32x16_bf16 v[112:127], v[136:139], v[156:159], v[112:127]
	v_mfma_f32_32x32x16_bf16 v[96:111], v[136:139], v[232:235], v[96:111]
	v_mfma_f32_32x32x16_bf16 v[48:63], v[148:151], v[156:159], v[48:63]
	v_mfma_f32_32x32x16_bf16 v[32:47], v[148:151], v[232:235], v[32:47]
	global_load_dwordx4 v[128:131], v[128:129], off offset:384
	s_nop 0
	global_load_dwordx4 v[136:139], v[132:133], off offset:384
	global_load_dwordx4 v[140:143], v[134:135], off offset:384
	s_nop 0
	global_load_dwordx4 v[144:147], v[144:145], off offset:384
	s_nop 0
	global_load_dwordx4 v[132:135], v[152:153], off offset:384
	global_load_dwordx4 v[148:151], v[154:155], off offset:384
	s_nop 0
	global_load_dwordx4 v[152:155], v[240:241], off offset:384
	s_waitcnt lgkmcnt(0)
	v_mfma_f32_32x32x16_bf16 v[16:31], v[236:239], v[156:159], v[16:31]
	global_load_dwordx4 v[156:159], v[242:243], off offset:384
	s_waitcnt vmcnt(15)
	ds_write_b128 v192, v[160:163]
	s_waitcnt vmcnt(14)
	ds_write_b128 v216, v[164:167]
	s_waitcnt vmcnt(13)
	ds_write_b128 v217, v[168:171]
	s_waitcnt vmcnt(12)
	ds_write_b128 v218, v[172:175]
	s_waitcnt vmcnt(11)
	ds_write_b128 v192, v[176:179] offset:36864
	s_waitcnt vmcnt(10)
	ds_write_b128 v216, v[180:183] offset:36864
	s_waitcnt vmcnt(9)
	ds_write_b128 v217, v[184:187] offset:36864
	s_waitcnt vmcnt(8)
	ds_write_b128 v218, v[188:191] offset:36864
	s_waitcnt lgkmcnt(0)
	s_barrier
	v_mfma_f32_32x32x16_bf16 v[0:15], v[236:239], v[232:235], v[0:15]
	s_cbranch_vccnz .LBB0_866
	s_waitcnt vmcnt(0)
	s_mov_b32 s22, s12
	s_mov_b32 s24, s13
	v_readlane_b32 s80, v253, 0
	v_readlane_b32 s81, v253, 1
	s_add_i32 s11, s11, 1
	s_mul_i32 s4, s11, s51
	s_add_i32 s4, s4, s50
	s_barrier
; DI void phase_wo(const Params& p, char* smem) {
;     ...
; #pragma unroll
;     for (int i = 0; i < 4; ++i)
; #pragma unroll
;       for (int j = 0; j < 2; ++j)
; #pragma unroll
;         for (int q4 = 0; q4 < 4; ++q4) {
;           const int f = n0 + wm * 128 + i * 32 + q4 * 8 + hh * 4;
;           const size_t t = m0 + wn * 64 + j * 32 + lr;
;           float4 xv = *(const float4*)(p.x + t * 1024 + f);
;           xv.x += acc[i][j][q4 * 4 + 0]; xv.y += acc[i][j][q4 * 4 + 1];
;           xv.z += acc[i][j][q4 * 4 + 2]; xv.w += acc[i][j][q4 * 4 + 3];
;           *(float4*)(X1 + t * 1024 + f) = xv;
;         }
	v_mbcnt_lo_u32_b32 v176, -1, 0
	v_mbcnt_hi_u32_b32 v176, -1, v176
	v_lshrrev_b32_e32 v177, 6, v211
	v_and_b32_e32 v178, 31, v176
	v_lshrrev_b32_e32 v179, 5, v176
	v_and_b32_e32 v180, 3, v177
	v_lshrrev_b32_e32 v181, 2, v177
	v_mul_u32_u24_e32 v182, 16896, v177
	v_mul_u32_u24_e32 v183, 528, v178
	v_lshl_add_u32 v183, v179, 4, v183
	v_add3_u32 v183, v183, v182, 64
	v_mul_u32_u24_e32 v184, 528, v179
	v_lshl_add_u32 v184, v178, 4, v184
	v_add3_u32 v184, v184, v182, 64
	v_lshl_add_u32 v185, v180, 6, v179
	v_add_u32_e32 v185, s22, v185
	v_lshlrev_b32_e32 v185, 12, v185
	v_lshlrev_b32_e32 v186, 9, v181
	v_lshl_add_u32 v186, v178, 4, v186
	s_lshl_b32 s26, s24, 2
	v_add3_u32 v185, v185, v186, s26
	v_mov_b32_e32 v187, v185
	ds_write_b128 v183, v[112:115] offset:0
	ds_write_b128 v183, v[116:119] offset:32
	ds_write_b128 v183, v[120:123] offset:64
	ds_write_b128 v183, v[124:127] offset:96
	ds_write_b128 v183, v[80:83] offset:128
	ds_write_b128 v183, v[84:87] offset:160
	ds_write_b128 v183, v[88:91] offset:192
	ds_write_b128 v183, v[92:95] offset:224
	ds_write_b128 v183, v[48:51] offset:256
	ds_write_b128 v183, v[52:55] offset:288
	ds_write_b128 v183, v[56:59] offset:320
	ds_write_b128 v183, v[60:63] offset:352
	ds_write_b128 v183, v[16:19] offset:384
	ds_write_b128 v183, v[20:23] offset:416
	ds_write_b128 v183, v[24:27] offset:448
	ds_write_b128 v183, v[28:31] offset:480
	global_load_dwordx4 v[144:147], v185, s[80:81]
	v_add_u32_e32 v185, 0x2000, v185
	global_load_dwordx4 v[148:151], v185, s[80:81]
	v_add_u32_e32 v185, 0x2000, v185
	global_load_dwordx4 v[152:155], v185, s[80:81]
	v_add_u32_e32 v185, 0x2000, v185
	global_load_dwordx4 v[156:159], v185, s[80:81]
	v_add_u32_e32 v185, 0x2000, v185
	global_load_dwordx4 v[160:163], v185, s[80:81]
	v_add_u32_e32 v185, 0x2000, v185
	global_load_dwordx4 v[164:167], v185, s[80:81]
	v_add_u32_e32 v185, 0x2000, v185
	global_load_dwordx4 v[168:171], v185, s[80:81]
	v_add_u32_e32 v185, 0x2000, v185
	global_load_dwordx4 v[172:175], v185, s[80:81]
	v_add_u32_e32 v185, 0x2000, v185
	ds_read_b128 v[128:131], v184 offset:0
	ds_read_b128 v[132:135], v184 offset:1056
	ds_read_b128 v[136:139], v184 offset:2112
	ds_read_b128 v[140:143], v184 offset:3168
	s_waitcnt vmcnt(4) lgkmcnt(0)
	v_pk_add_f32 v[128:129], v[128:129], v[144:145]
	v_pk_add_f32 v[130:131], v[130:131], v[146:147]
	v_pk_add_f32 v[132:133], v[132:133], v[148:149]
	v_pk_add_f32 v[134:135], v[134:135], v[150:151]
	v_pk_add_f32 v[136:137], v[136:137], v[152:153]
	v_pk_add_f32 v[138:139], v[138:139], v[154:155]
	v_pk_add_f32 v[140:141], v[140:141], v[156:157]
	v_pk_add_f32 v[142:143], v[142:143], v[158:159]
	global_store_dwordx4 v187, v[128:131], s[76:77]
	v_add_u32_e32 v187, 0x2000, v187
	global_store_dwordx4 v187, v[132:135], s[76:77]
	v_add_u32_e32 v187, 0x2000, v187
	global_store_dwordx4 v187, v[136:139], s[76:77]
	v_add_u32_e32 v187, 0x2000, v187
	global_store_dwordx4 v187, v[140:143], s[76:77]
	v_add_u32_e32 v187, 0x2000, v187
	global_load_dwordx4 v[144:147], v185, s[80:81]
	v_add_u32_e32 v185, 0x2000, v185
	global_load_dwordx4 v[148:151], v185, s[80:81]
	v_add_u32_e32 v185, 0x2000, v185
	global_load_dwordx4 v[152:155], v185, s[80:81]
	v_add_u32_e32 v185, 0x2000, v185
	global_load_dwordx4 v[156:159], v185, s[80:81]
	v_add_u32_e32 v185, 0x2000, v185
	ds_read_b128 v[128:131], v184 offset:4224
	ds_read_b128 v[132:135], v184 offset:5280
	ds_read_b128 v[136:139], v184 offset:6336
	ds_read_b128 v[140:143], v184 offset:7392
	s_waitcnt vmcnt(8) lgkmcnt(0)
	v_pk_add_f32 v[128:129], v[128:129], v[160:161]
	v_pk_add_f32 v[130:131], v[130:131], v[162:163]
	v_pk_add_f32 v[132:133], v[132:133], v[164:165]
	v_pk_add_f32 v[134:135], v[134:135], v[166:167]
	v_pk_add_f32 v[136:137], v[136:137], v[168:169]
	v_pk_add_f32 v[138:139], v[138:139], v[170:171]
	v_pk_add_f32 v[140:141], v[140:141], v[172:173]
	v_pk_add_f32 v[142:143], v[142:143], v[174:175]
	global_store_dwordx4 v187, v[128:131], s[76:77]
	v_add_u32_e32 v187, 0x2000, v187
	global_store_dwordx4 v187, v[132:135], s[76:77]
	v_add_u32_e32 v187, 0x2000, v187
	global_store_dwordx4 v187, v[136:139], s[76:77]
	v_add_u32_e32 v187, 0x2000, v187
	global_store_dwordx4 v187, v[140:143], s[76:77]
	v_add_u32_e32 v187, 0x2000, v187
	global_load_dwordx4 v[160:163], v185, s[80:81]
	v_add_u32_e32 v185, 0x2000, v185
	global_load_dwordx4 v[164:167], v185, s[80:81]
	v_add_u32_e32 v185, 0x2000, v185
	global_load_dwordx4 v[168:171], v185, s[80:81]
	v_add_u32_e32 v185, 0x2000, v185
	global_load_dwordx4 v[172:175], v185, s[80:81]
	v_add_u32_e32 v185, 0x2000, v185
	ds_read_b128 v[128:131], v184 offset:8448
	ds_read_b128 v[132:135], v184 offset:9504
	ds_read_b128 v[136:139], v184 offset:10560
	ds_read_b128 v[140:143], v184 offset:11616
	s_waitcnt vmcnt(8) lgkmcnt(0)
	v_pk_add_f32 v[128:129], v[128:129], v[144:145]
	v_pk_add_f32 v[130:131], v[130:131], v[146:147]
	v_pk_add_f32 v[132:133], v[132:133], v[148:149]
	v_pk_add_f32 v[134:135], v[134:135], v[150:151]
	v_pk_add_f32 v[136:137], v[136:137], v[152:153]
	v_pk_add_f32 v[138:139], v[138:139], v[154:155]
	v_pk_add_f32 v[140:141], v[140:141], v[156:157]
	v_pk_add_f32 v[142:143], v[142:143], v[158:159]
	global_store_dwordx4 v187, v[128:131], s[76:77]
	v_add_u32_e32 v187, 0x2000, v187
	global_store_dwordx4 v187, v[132:135], s[76:77]
	v_add_u32_e32 v187, 0x2000, v187
	global_store_dwordx4 v187, v[136:139], s[76:77]
	v_add_u32_e32 v187, 0x2000, v187
	global_store_dwordx4 v187, v[140:143], s[76:77]
	v_add_u32_e32 v187, 0x2000, v187
	global_load_dwordx4 v[144:147], v185, s[80:81]
	v_add_u32_e32 v185, 0x2000, v185
	global_load_dwordx4 v[148:151], v185, s[80:81]
	v_add_u32_e32 v185, 0x2000, v185
	global_load_dwordx4 v[152:155], v185, s[80:81]
	v_add_u32_e32 v185, 0x2000, v185
	global_load_dwordx4 v[156:159], v185, s[80:81]
	v_add_u32_e32 v185, 0x2000, v185
	ds_read_b128 v[128:131], v184 offset:12672
	ds_read_b128 v[132:135], v184 offset:13728
	ds_read_b128 v[136:139], v184 offset:14784
	ds_read_b128 v[140:143], v184 offset:15840
	s_waitcnt vmcnt(8) lgkmcnt(0)
; DI void phase_wo(const Params& p, char* smem) {
;     ...
; #pragma unroll
;     for (int i = 0; i < 4; ++i)
; #pragma unroll
;       for (int j = 0; j < 2; ++j)
; #pragma unroll
;         for (int q4 = 0; q4 < 4; ++q4) {
;           const int f = n0 + wm * 128 + i * 32 + q4 * 8 + hh * 4;
;           const size_t t = m0 + wn * 64 + j * 32 + lr;
;           float4 xv = *(const float4*)(p.x + t * 1024 + f);
;           xv.x += acc[i][j][q4 * 4 + 0]; xv.y += acc[i][j][q4 * 4 + 1];
;           xv.z += acc[i][j][q4 * 4 + 2]; xv.w += acc[i][j][q4 * 4 + 3];
;           *(float4*)(X1 + t * 1024 + f) = xv;
;         }
	v_pk_add_f32 v[128:129], v[128:129], v[160:161]
	v_pk_add_f32 v[130:131], v[130:131], v[162:163]
	v_pk_add_f32 v[132:133], v[132:133], v[164:165]
	v_pk_add_f32 v[134:135], v[134:135], v[166:167]
	v_pk_add_f32 v[136:137], v[136:137], v[168:169]
	v_pk_add_f32 v[138:139], v[138:139], v[170:171]
	v_pk_add_f32 v[140:141], v[140:141], v[172:173]
	v_pk_add_f32 v[142:143], v[142:143], v[174:175]
	global_store_dwordx4 v187, v[128:131], s[76:77]
	v_add_u32_e32 v187, 0x2000, v187
	global_store_dwordx4 v187, v[132:135], s[76:77]
	v_add_u32_e32 v187, 0x2000, v187
	global_store_dwordx4 v187, v[136:139], s[76:77]
	v_add_u32_e32 v187, 0x2000, v187
	global_store_dwordx4 v187, v[140:143], s[76:77]
	v_add_u32_e32 v187, 0x2000, v187
	ds_write_b128 v183, v[96:99] offset:0
	ds_write_b128 v183, v[100:103] offset:32
	ds_write_b128 v183, v[104:107] offset:64
	ds_write_b128 v183, v[108:111] offset:96
	ds_write_b128 v183, v[64:67] offset:128
	ds_write_b128 v183, v[68:71] offset:160
	ds_write_b128 v183, v[72:75] offset:192
	ds_write_b128 v183, v[76:79] offset:224
	ds_write_b128 v183, v[32:35] offset:256
	ds_write_b128 v183, v[36:39] offset:288
	ds_write_b128 v183, v[40:43] offset:320
	ds_write_b128 v183, v[44:47] offset:352
	ds_write_b128 v183, v[0:3] offset:384
	ds_write_b128 v183, v[4:7] offset:416
	ds_write_b128 v183, v[8:11] offset:448
	ds_write_b128 v183, v[12:15] offset:480
	global_load_dwordx4 v[160:163], v185, s[80:81]
	v_add_u32_e32 v185, 0x2000, v185
	global_load_dwordx4 v[164:167], v185, s[80:81]
	v_add_u32_e32 v185, 0x2000, v185
	global_load_dwordx4 v[168:171], v185, s[80:81]
	v_add_u32_e32 v185, 0x2000, v185
	global_load_dwordx4 v[172:175], v185, s[80:81]
	v_add_u32_e32 v185, 0x2000, v185
	ds_read_b128 v[128:131], v184 offset:0
	ds_read_b128 v[132:135], v184 offset:1056
	ds_read_b128 v[136:139], v184 offset:2112
	ds_read_b128 v[140:143], v184 offset:3168
	s_waitcnt vmcnt(8) lgkmcnt(0)
	v_pk_add_f32 v[128:129], v[128:129], v[144:145]
	v_pk_add_f32 v[130:131], v[130:131], v[146:147]
	v_pk_add_f32 v[132:133], v[132:133], v[148:149]
	v_pk_add_f32 v[134:135], v[134:135], v[150:151]
	v_pk_add_f32 v[136:137], v[136:137], v[152:153]
	v_pk_add_f32 v[138:139], v[138:139], v[154:155]
	v_pk_add_f32 v[140:141], v[140:141], v[156:157]
	v_pk_add_f32 v[142:143], v[142:143], v[158:159]
	global_store_dwordx4 v187, v[128:131], s[76:77]
	v_add_u32_e32 v187, 0x2000, v187
	global_store_dwordx4 v187, v[132:135], s[76:77]
	v_add_u32_e32 v187, 0x2000, v187
	global_store_dwordx4 v187, v[136:139], s[76:77]
	v_add_u32_e32 v187, 0x2000, v187
	global_store_dwordx4 v187, v[140:143], s[76:77]
	v_add_u32_e32 v187, 0x2000, v187
	global_load_dwordx4 v[144:147], v185, s[80:81]
	v_add_u32_e32 v185, 0x2000, v185
	global_load_dwordx4 v[148:151], v185, s[80:81]
	v_add_u32_e32 v185, 0x2000, v185
	global_load_dwordx4 v[152:155], v185, s[80:81]
	v_add_u32_e32 v185, 0x2000, v185
	global_load_dwordx4 v[156:159], v185, s[80:81]
	v_add_u32_e32 v185, 0x2000, v185
	ds_read_b128 v[128:131], v184 offset:4224
	ds_read_b128 v[132:135], v184 offset:5280
	ds_read_b128 v[136:139], v184 offset:6336
	ds_read_b128 v[140:143], v184 offset:7392
	s_waitcnt vmcnt(8) lgkmcnt(0)
	v_pk_add_f32 v[128:129], v[128:129], v[160:161]
	v_pk_add_f32 v[130:131], v[130:131], v[162:163]
	v_pk_add_f32 v[132:133], v[132:133], v[164:165]
	v_pk_add_f32 v[134:135], v[134:135], v[166:167]
	v_pk_add_f32 v[136:137], v[136:137], v[168:169]
	v_pk_add_f32 v[138:139], v[138:139], v[170:171]
	v_pk_add_f32 v[140:141], v[140:141], v[172:173]
	v_pk_add_f32 v[142:143], v[142:143], v[174:175]
	global_store_dwordx4 v187, v[128:131], s[76:77]
	v_add_u32_e32 v187, 0x2000, v187
	global_store_dwordx4 v187, v[132:135], s[76:77]
	v_add_u32_e32 v187, 0x2000, v187
	global_store_dwordx4 v187, v[136:139], s[76:77]
	v_add_u32_e32 v187, 0x2000, v187
	global_store_dwordx4 v187, v[140:143], s[76:77]
	v_add_u32_e32 v187, 0x2000, v187
	global_load_dwordx4 v[160:163], v185, s[80:81]
	v_add_u32_e32 v185, 0x2000, v185
	global_load_dwordx4 v[164:167], v185, s[80:81]
	v_add_u32_e32 v185, 0x2000, v185
	global_load_dwordx4 v[168:171], v185, s[80:81]
	v_add_u32_e32 v185, 0x2000, v185
	global_load_dwordx4 v[172:175], v185, s[80:81]
	v_add_u32_e32 v185, 0x2000, v185
	ds_read_b128 v[128:131], v184 offset:8448
	ds_read_b128 v[132:135], v184 offset:9504
	ds_read_b128 v[136:139], v184 offset:10560
	ds_read_b128 v[140:143], v184 offset:11616
	s_waitcnt vmcnt(8) lgkmcnt(0)
	v_pk_add_f32 v[128:129], v[128:129], v[144:145]
	v_pk_add_f32 v[130:131], v[130:131], v[146:147]
	v_pk_add_f32 v[132:133], v[132:133], v[148:149]
	v_pk_add_f32 v[134:135], v[134:135], v[150:151]
	v_pk_add_f32 v[136:137], v[136:137], v[152:153]
	v_pk_add_f32 v[138:139], v[138:139], v[154:155]
	v_pk_add_f32 v[140:141], v[140:141], v[156:157]
	v_pk_add_f32 v[142:143], v[142:143], v[158:159]
	global_store_dwordx4 v187, v[128:131], s[76:77]
	v_add_u32_e32 v187, 0x2000, v187
	global_store_dwordx4 v187, v[132:135], s[76:77]
	v_add_u32_e32 v187, 0x2000, v187
	global_store_dwordx4 v187, v[136:139], s[76:77]
	v_add_u32_e32 v187, 0x2000, v187
	global_store_dwordx4 v187, v[140:143], s[76:77]
	v_add_u32_e32 v187, 0x2000, v187
	ds_read_b128 v[128:131], v184 offset:12672
	ds_read_b128 v[132:135], v184 offset:13728
	ds_read_b128 v[136:139], v184 offset:14784
	ds_read_b128 v[140:143], v184 offset:15840
	s_waitcnt vmcnt(4) lgkmcnt(0)
	v_pk_add_f32 v[128:129], v[128:129], v[160:161]
	v_pk_add_f32 v[130:131], v[130:131], v[162:163]
	v_pk_add_f32 v[132:133], v[132:133], v[164:165]
	v_pk_add_f32 v[134:135], v[134:135], v[166:167]
	v_pk_add_f32 v[136:137], v[136:137], v[168:169]
	v_pk_add_f32 v[138:139], v[138:139], v[170:171]
	v_pk_add_f32 v[140:141], v[140:141], v[172:173]
	v_pk_add_f32 v[142:143], v[142:143], v[174:175]
	global_store_dwordx4 v187, v[128:131], s[76:77]
	v_add_u32_e32 v187, 0x2000, v187
	global_store_dwordx4 v187, v[132:135], s[76:77]
	v_add_u32_e32 v187, 0x2000, v187
	global_store_dwordx4 v187, v[136:139], s[76:77]
	v_add_u32_e32 v187, 0x2000, v187
	global_store_dwordx4 v187, v[140:143], s[76:77]
	v_add_u32_e32 v187, 0x2000, v187
	s_cmp_lt_u32 s4, 32
	s_cbranch_scc1 .LBB0_865
	s_mov_b32 s88, s17

; template <int WM, class AF, class BF>
; DI void gemm512(f32x16 (&acc)[WM][2], AF arow, int a_kstep, BF brow, int b_kstep, int KT, char* smem) {
;     ...
; #pragma unroll 1
;   for (int kt = 0; kt < KT; kt += 2) {
;     GEMM_STEP(A0, B0, A1, B1, ra0, rb0, ra1, rb1, kt + 2)
;     if (kt + 1 < KT) GEMM_STEP(A1, B1, A0, B0, ra1, rb1, ra0, rb0, kt + 3)
;   }
.LBB0_979:
	ds_read_b128 v[160:163], v220
	ds_read_b128 v[164:167], v219 offset:36864
	ds_read_b128 v[168:171], v219 offset:36896
	ds_read_b128 v[172:175], v220 offset:32
	ds_read_b128 v[176:179], v219 offset:41472
	ds_read_b128 v[180:183], v219 offset:41504
	s_add_i32 s22, s15, 2
	s_waitcnt lgkmcnt(4)
	v_mfma_f32_32x32x16_bf16 v[112:127], v[160:163], v[164:167], v[112:127]
	s_cmp_lt_u32 s15, 14
	s_cselect_b64 s[24:25], -1, 0
	s_and_b64 vcc, s[24:25], exec
	s_cselect_b32 s2, s14, 0x3c0
	s_lshl_b64 s[24:25], s[2:3], 1
	s_min_u32 s2, s15, 12
	s_lshl_b32 s2, s2, 7
	s_waitcnt lgkmcnt(1)
	v_mfma_f32_32x32x16_bf16 v[96:111], v[160:163], v[176:179], v[96:111]
	ds_read_b128 v[160:163], v220 offset:4608
	ds_read_b128 v[184:187], v220 offset:4640
	v_lshl_add_u64 v[240:241], v[206:207], 0, s[2:3]
	v_lshl_add_u64 v[242:243], v[208:209], 0, s[2:3]
	s_addk_i32 s14, 0x80
	s_mov_b32 s15, s22
	s_waitcnt lgkmcnt(1)
	v_mfma_f32_32x32x16_bf16 v[80:95], v[160:163], v[164:167], v[80:95]
	v_mfma_f32_32x32x16_bf16 v[64:79], v[160:163], v[176:179], v[64:79]
	ds_read_b128 v[160:163], v220 offset:9216
	ds_read_b128 v[188:191], v220 offset:9248
	s_waitcnt lgkmcnt(1)
	v_mfma_f32_32x32x16_bf16 v[48:63], v[160:163], v[164:167], v[48:63]
	v_mfma_f32_32x32x16_bf16 v[32:47], v[160:163], v[176:179], v[32:47]
	ds_read_b128 v[160:163], v220 offset:13824
	ds_read_b128 v[232:235], v220 offset:13856
	s_waitcnt lgkmcnt(1)
	v_mfma_f32_32x32x16_bf16 v[16:31], v[160:163], v[164:167], v[16:31]
	v_mfma_f32_32x32x16_bf16 v[0:15], v[160:163], v[176:179], v[0:15]
	v_mfma_f32_32x32x16_bf16 v[112:127], v[172:175], v[168:171], v[112:127]
	v_mfma_f32_32x32x16_bf16 v[96:111], v[172:175], v[180:183], v[96:111]
	v_mfma_f32_32x32x16_bf16 v[80:95], v[184:187], v[168:171], v[80:95]
	v_mfma_f32_32x32x16_bf16 v[64:79], v[184:187], v[180:183], v[64:79]
	v_mfma_f32_32x32x16_bf16 v[48:63], v[188:191], v[168:171], v[48:63]
	s_waitcnt lgkmcnt(0)
	v_mfma_f32_32x32x16_bf16 v[16:31], v[232:235], v[168:171], v[16:31]
	ds_read_b128 v[160:163], v220 offset:64
	ds_read_b128 v[164:167], v219 offset:36928
	ds_read_b128 v[176:179], v219 offset:36960
	ds_read_b128 v[168:171], v220 offset:96
	v_mfma_f32_32x32x16_bf16 v[0:15], v[232:235], v[180:183], v[0:15]
	ds_read_b128 v[172:175], v219 offset:41536
	ds_read_b128 v[232:235], v219 offset:41568
	v_mfma_f32_32x32x16_bf16 v[32:47], v[188:191], v[180:183], v[32:47]
	s_waitcnt lgkmcnt(4)
	v_mfma_f32_32x32x16_bf16 v[112:127], v[160:163], v[164:167], v[112:127]
	s_waitcnt lgkmcnt(1)
	v_mfma_f32_32x32x16_bf16 v[96:111], v[160:163], v[172:175], v[96:111]
	ds_read_b128 v[160:163], v220 offset:4672
	ds_read_b128 v[180:183], v220 offset:4704
	s_waitcnt lgkmcnt(1)
	v_mfma_f32_32x32x16_bf16 v[80:95], v[160:163], v[164:167], v[80:95]
	v_mfma_f32_32x32x16_bf16 v[64:79], v[160:163], v[172:175], v[64:79]
	ds_read_b128 v[160:163], v220 offset:9280
	ds_read_b128 v[184:187], v220 offset:9312
	s_waitcnt lgkmcnt(1)
	v_mfma_f32_32x32x16_bf16 v[48:63], v[160:163], v[164:167], v[48:63]
	v_mfma_f32_32x32x16_bf16 v[32:47], v[160:163], v[172:175], v[32:47]
	ds_read_b128 v[160:163], v220 offset:13888
	ds_read_b128 v[236:239], v220 offset:13920
	s_waitcnt vmcnt(7)
	ds_write_b128 v223, v[128:131]
	s_waitcnt vmcnt(5)
	ds_write_b128 v224, v[136:139]
	s_waitcnt vmcnt(4)
	ds_write_b128 v225, v[140:143]
	s_waitcnt vmcnt(3)
	ds_write_b128 v226, v[144:147]
	ds_write_b128 v227, v[132:135]
	s_waitcnt vmcnt(2)
	ds_write_b128 v228, v[148:151]
	s_waitcnt vmcnt(1)
	ds_write_b128 v229, v[152:155]
	s_waitcnt vmcnt(0)
	ds_write_b128 v230, v[156:159]
	v_lshl_add_u64 v[128:129], v[194:195], 0, s[24:25]
	v_lshl_add_u64 v[130:131], v[196:197], 0, s[24:25]
	v_lshl_add_u64 v[132:133], v[198:199], 0, s[24:25]
	v_lshl_add_u64 v[134:135], v[200:201], 0, s[24:25]
	s_waitcnt lgkmcnt(9)
	v_mfma_f32_32x32x16_bf16 v[16:31], v[160:163], v[164:167], v[16:31]
	v_lshl_add_u64 v[136:137], v[202:203], 0, s[24:25]
	v_lshl_add_u64 v[138:139], v[204:205], 0, s[24:25]
	v_lshl_add_u64 v[140:141], v[206:207], 0, s[24:25]
	v_lshl_add_u64 v[142:143], v[208:209], 0, s[24:25]
	v_mfma_f32_32x32x16_bf16 v[112:127], v[168:171], v[176:179], v[112:127]
	v_mfma_f32_32x32x16_bf16 v[96:111], v[168:171], v[232:235], v[96:111]
	v_mfma_f32_32x32x16_bf16 v[0:15], v[160:163], v[172:175], v[0:15]
	global_load_dwordx4 v[160:163], v[128:129], off
	global_load_dwordx4 v[164:167], v[130:131], off
	global_load_dwordx4 v[168:171], v[132:133], off
	global_load_dwordx4 v[172:175], v[134:135], off
	v_mfma_f32_32x32x16_bf16 v[80:95], v[180:183], v[176:179], v[80:95]
	v_mfma_f32_32x32x16_bf16 v[64:79], v[180:183], v[232:235], v[64:79]
	v_mfma_f32_32x32x16_bf16 v[48:63], v[184:187], v[176:179], v[48:63]
	v_mfma_f32_32x32x16_bf16 v[32:47], v[184:187], v[232:235], v[32:47]
	s_waitcnt lgkmcnt(8)
	v_mfma_f32_32x32x16_bf16 v[16:31], v[236:239], v[176:179], v[16:31]
	global_load_dwordx4 v[176:179], v[136:137], off
	global_load_dwordx4 v[180:183], v[138:139], off
	global_load_dwordx4 v[184:187], v[140:141], off
	global_load_dwordx4 v[188:191], v[142:143], off
	s_waitcnt lgkmcnt(0)
	s_barrier
; template <int WM, class AF, class BF>
; DI void gemm512(f32x16 (&acc)[WM][2], AF arow, int a_kstep, BF brow, int b_kstep, int KT, char* smem) {
;     ...
; #pragma unroll 1
;   for (int kt = 0; kt < KT; kt += 2) {
;     GEMM_STEP(A0, B0, A1, B1, ra0, rb0, ra1, rb1, kt + 2)
;     if (kt + 1 < KT) GEMM_STEP(A1, B1, A0, B0, ra1, rb1, ra0, rb0, kt + 3)
;   }
	ds_read_b128 v[128:131], v222
	ds_read_b128 v[132:135], v221
	ds_read_b128 v[136:139], v221 offset:32
	ds_read_b128 v[140:143], v222 offset:32
	ds_read_b128 v[144:147], v221 offset:4608
	ds_read_b128 v[148:151], v221 offset:4640
	s_waitcnt lgkmcnt(4)
	v_mfma_f32_32x32x16_bf16 v[112:127], v[128:131], v[132:135], v[112:127]
	s_waitcnt lgkmcnt(1)
	v_mfma_f32_32x32x16_bf16 v[96:111], v[128:131], v[144:147], v[96:111]
	ds_read_b128 v[128:131], v222 offset:4608
	ds_read_b128 v[152:155], v222 offset:4640
	v_mfma_f32_32x32x16_bf16 v[0:15], v[236:239], v[232:235], v[0:15]
	s_waitcnt lgkmcnt(1)
	v_mfma_f32_32x32x16_bf16 v[80:95], v[128:131], v[132:135], v[80:95]
	v_mfma_f32_32x32x16_bf16 v[64:79], v[128:131], v[144:147], v[64:79]
	ds_read_b128 v[128:131], v222 offset:9216
	ds_read_b128 v[156:159], v222 offset:9248
	s_waitcnt lgkmcnt(1)
	v_mfma_f32_32x32x16_bf16 v[48:63], v[128:131], v[132:135], v[48:63]
	v_mfma_f32_32x32x16_bf16 v[32:47], v[128:131], v[144:147], v[32:47]
	ds_read_b128 v[128:131], v222 offset:13824
	ds_read_b128 v[232:235], v222 offset:13856
	s_waitcnt lgkmcnt(1)
	v_mfma_f32_32x32x16_bf16 v[16:31], v[128:131], v[132:135], v[16:31]
	v_mfma_f32_32x32x16_bf16 v[0:15], v[128:131], v[144:147], v[0:15]
	v_mfma_f32_32x32x16_bf16 v[112:127], v[140:143], v[136:139], v[112:127]
	v_mfma_f32_32x32x16_bf16 v[96:111], v[140:143], v[148:151], v[96:111]
	v_mfma_f32_32x32x16_bf16 v[80:95], v[152:155], v[136:139], v[80:95]
	v_mfma_f32_32x32x16_bf16 v[64:79], v[152:155], v[148:151], v[64:79]
	v_lshl_add_u64 v[152:153], v[202:203], 0, s[2:3]
	v_lshl_add_u64 v[154:155], v[204:205], 0, s[2:3]
	v_mfma_f32_32x32x16_bf16 v[48:63], v[156:159], v[136:139], v[48:63]
	v_mfma_f32_32x32x16_bf16 v[32:47], v[156:159], v[148:151], v[32:47]
	s_waitcnt lgkmcnt(0)
	v_mfma_f32_32x32x16_bf16 v[16:31], v[232:235], v[136:139], v[16:31]
	ds_read_b128 v[128:131], v222 offset:64
	ds_read_b128 v[132:135], v221 offset:64
	ds_read_b128 v[156:159], v221 offset:96
	ds_read_b128 v[136:139], v222 offset:96
	v_mfma_f32_32x32x16_bf16 v[0:15], v[232:235], v[148:151], v[0:15]
	ds_read_b128 v[140:143], v221 offset:4672
	ds_read_b128 v[232:235], v221 offset:4704
	s_waitcnt lgkmcnt(4)
	v_mfma_f32_32x32x16_bf16 v[112:127], v[128:131], v[132:135], v[112:127]
	s_waitcnt lgkmcnt(1)
	v_mfma_f32_32x32x16_bf16 v[96:111], v[128:131], v[140:143], v[96:111]
	ds_read_b128 v[128:131], v222 offset:4672
	ds_read_b128 v[144:147], v222 offset:4704
	s_waitcnt lgkmcnt(1)
	v_mfma_f32_32x32x16_bf16 v[80:95], v[128:131], v[132:135], v[80:95]
	v_mfma_f32_32x32x16_bf16 v[64:79], v[128:131], v[140:143], v[64:79]
	ds_read_b128 v[128:131], v222 offset:9280
	ds_read_b128 v[148:151], v222 offset:9312
	s_waitcnt lgkmcnt(1)
	v_mfma_f32_32x32x16_bf16 v[48:63], v[128:131], v[132:135], v[48:63]
	v_mfma_f32_32x32x16_bf16 v[32:47], v[128:131], v[140:143], v[32:47]
	ds_read_b128 v[128:131], v222 offset:13888
	ds_read_b128 v[236:239], v222 offset:13920
	s_waitcnt lgkmcnt(1)
	v_mfma_f32_32x32x16_bf16 v[16:31], v[128:131], v[132:135], v[16:31]
	v_lshl_add_u64 v[132:133], v[196:197], 0, s[2:3]
	v_lshl_add_u64 v[134:135], v[198:199], 0, s[2:3]
	v_mfma_f32_32x32x16_bf16 v[0:15], v[128:131], v[140:143], v[0:15]
	v_lshl_add_u64 v[128:129], v[194:195], 0, s[2:3]
	v_mfma_f32_32x32x16_bf16 v[80:95], v[144:147], v[156:159], v[80:95]
	v_mfma_f32_32x32x16_bf16 v[64:79], v[144:147], v[232:235], v[64:79]
	v_lshl_add_u64 v[144:145], v[200:201], 0, s[2:3]
	v_mfma_f32_32x32x16_bf16 v[112:127], v[136:139], v[156:159], v[112:127]
	v_mfma_f32_32x32x16_bf16 v[96:111], v[136:139], v[232:235], v[96:111]
	v_mfma_f32_32x32x16_bf16 v[48:63], v[148:151], v[156:159], v[48:63]
	v_mfma_f32_32x32x16_bf16 v[32:47], v[148:151], v[232:235], v[32:47]
	global_load_dwordx4 v[128:131], v[128:129], off offset:384
	s_nop 0
	global_load_dwordx4 v[136:139], v[132:133], off offset:384
	global_load_dwordx4 v[140:143], v[134:135], off offset:384
	s_nop 0
	global_load_dwordx4 v[144:147], v[144:145], off offset:384
	s_nop 0
	global_load_dwordx4 v[132:135], v[152:153], off offset:384
	global_load_dwordx4 v[148:151], v[154:155], off offset:384
	s_nop 0
	global_load_dwordx4 v[152:155], v[240:241], off offset:384
	s_waitcnt lgkmcnt(0)
	v_mfma_f32_32x32x16_bf16 v[16:31], v[236:239], v[156:159], v[16:31]
	global_load_dwordx4 v[156:159], v[242:243], off offset:384
	s_waitcnt vmcnt(15)
	ds_write_b128 v192, v[160:163]
	s_waitcnt vmcnt(14)
	ds_write_b128 v216, v[164:167]
	s_waitcnt vmcnt(13)
	ds_write_b128 v217, v[168:171]
	s_waitcnt vmcnt(12)
	ds_write_b128 v218, v[172:175]
	s_waitcnt vmcnt(11)
	ds_write_b128 v192, v[176:179] offset:36864
	s_waitcnt vmcnt(10)
	ds_write_b128 v216, v[180:183] offset:36864
	s_waitcnt vmcnt(9)
	ds_write_b128 v217, v[184:187] offset:36864
	s_waitcnt vmcnt(8)
	ds_write_b128 v218, v[188:191] offset:36864
	s_waitcnt lgkmcnt(0)
	s_barrier
	v_mfma_f32_32x32x16_bf16 v[0:15], v[236:239], v[232:235], v[0:15]
	s_cbranch_vccnz .LBB0_979
; DI void phase_pq(const Params& p, char* smem) {
;     ...
; #pragma unroll
;     for (int i = 0; i < 4; ++i)
; #pragma unroll
;       for (int j = 0; j < 2; ++j)
; #pragma unroll
;         for (int q4 = 0; q4 < 4; ++q4) {
;           const int f = n0 + wm * 128 + i * 32 + q4 * 8 + hh * 4;
;           const size_t t = m0 + wn * 64 + j * 32 + lr;
;           uint2 o;
;           o.x = pack2(acc[i][j][q4 * 4 + 0], acc[i][j][q4 * 4 + 1]);
;           o.y = pack2(acc[i][j][q4 * 4 + 2], acc[i][j][q4 * 4 + 3]);
;           *(uint2*)(PQ + t * 2048 + f) = o;
;         }
;   }
	s_waitcnt vmcnt(0)
	s_add_i32 s11, s11, 1
	s_mul_i32 s2, s11, s51
	s_add_i32 s2, s2, s50
	v_cvt_pk_bf16_f32 v112, v112, v113
	v_cvt_pk_bf16_f32 v113, v114, v115
	v_cvt_pk_bf16_f32 v114, v116, v117
	v_cvt_pk_bf16_f32 v115, v118, v119
	v_cvt_pk_bf16_f32 v116, v120, v121
	v_cvt_pk_bf16_f32 v117, v122, v123
	v_cvt_pk_bf16_f32 v118, v124, v125
	v_cvt_pk_bf16_f32 v119, v126, v127
	v_cvt_pk_bf16_f32 v96, v96, v97
	v_cvt_pk_bf16_f32 v97, v98, v99
	v_cvt_pk_bf16_f32 v98, v100, v101
	v_cvt_pk_bf16_f32 v99, v102, v103
	v_cvt_pk_bf16_f32 v100, v104, v105
	v_cvt_pk_bf16_f32 v101, v106, v107
	v_cvt_pk_bf16_f32 v102, v108, v109
	v_cvt_pk_bf16_f32 v103, v110, v111
	v_cvt_pk_bf16_f32 v80, v80, v81
	v_cvt_pk_bf16_f32 v81, v82, v83
	v_cvt_pk_bf16_f32 v82, v84, v85
	v_cvt_pk_bf16_f32 v83, v86, v87
	v_cvt_pk_bf16_f32 v84, v88, v89
	v_cvt_pk_bf16_f32 v85, v90, v91
	v_cvt_pk_bf16_f32 v86, v92, v93
	v_cvt_pk_bf16_f32 v87, v94, v95
	v_cvt_pk_bf16_f32 v64, v64, v65
	v_cvt_pk_bf16_f32 v65, v66, v67
	v_cvt_pk_bf16_f32 v66, v68, v69
	v_cvt_pk_bf16_f32 v67, v70, v71
	v_cvt_pk_bf16_f32 v68, v72, v73
	v_cvt_pk_bf16_f32 v69, v74, v75
	v_cvt_pk_bf16_f32 v70, v76, v77
	v_cvt_pk_bf16_f32 v71, v78, v79
	v_cvt_pk_bf16_f32 v48, v48, v49
	v_cvt_pk_bf16_f32 v49, v50, v51
	v_cvt_pk_bf16_f32 v50, v52, v53
	v_cvt_pk_bf16_f32 v51, v54, v55
	v_cvt_pk_bf16_f32 v52, v56, v57
	v_cvt_pk_bf16_f32 v53, v58, v59
	v_cvt_pk_bf16_f32 v54, v60, v61
	v_cvt_pk_bf16_f32 v55, v62, v63
	v_cvt_pk_bf16_f32 v32, v32, v33
	v_cvt_pk_bf16_f32 v33, v34, v35
	v_cvt_pk_bf16_f32 v34, v36, v37
	v_cvt_pk_bf16_f32 v35, v38, v39
	v_cvt_pk_bf16_f32 v36, v40, v41
	v_cvt_pk_bf16_f32 v37, v42, v43
	v_cvt_pk_bf16_f32 v38, v44, v45
	v_cvt_pk_bf16_f32 v39, v46, v47
	v_cvt_pk_bf16_f32 v16, v16, v17
	v_cvt_pk_bf16_f32 v17, v18, v19
	v_cvt_pk_bf16_f32 v18, v20, v21
	v_cvt_pk_bf16_f32 v19, v22, v23
	v_cvt_pk_bf16_f32 v20, v24, v25
	v_cvt_pk_bf16_f32 v21, v26, v27
	v_cvt_pk_bf16_f32 v22, v28, v29
	v_cvt_pk_bf16_f32 v23, v30, v31
	v_cvt_pk_bf16_f32 v0, v0, v1
	v_cvt_pk_bf16_f32 v1, v2, v3
	v_cvt_pk_bf16_f32 v2, v4, v5
	v_cvt_pk_bf16_f32 v3, v6, v7
	v_cvt_pk_bf16_f32 v4, v8, v9
	v_cvt_pk_bf16_f32 v5, v10, v11
	v_cvt_pk_bf16_f32 v6, v12, v13
	v_cvt_pk_bf16_f32 v7, v14, v15
	s_barrier
	v_mbcnt_lo_u32_b32 v128, -1, 0
	v_mbcnt_hi_u32_b32 v128, -1, v128
	v_lshrrev_b32_e32 v129, 6, v211
	v_and_b32_e32 v130, 31, v128
	v_lshrrev_b32_e32 v131, 5, v128
	v_and_b32_e32 v132, 3, v129
	v_lshrrev_b32_e32 v133, 2, v129
	v_lshl_add_u32 v134, v132, 6, v130
	v_mul_u32_u24_e32 v134, 528, v134
	v_lshlrev_b32_e32 v135, 8, v133
	v_lshl_add_u32 v135, v131, 3, v135
	v_add3_u32 v134, v134, v135, 64
	ds_write_b64 v134, v[112:113] offset:0
	ds_write_b64 v134, v[114:115] offset:16
	ds_write_b64 v134, v[116:117] offset:32
	ds_write_b64 v134, v[118:119] offset:48
	ds_write_b64 v134, v[96:97] offset:16896
	ds_write_b64 v134, v[98:99] offset:16912
	ds_write_b64 v134, v[100:101] offset:16928
	ds_write_b64 v134, v[102:103] offset:16944
	ds_write_b64 v134, v[80:81] offset:64
	ds_write_b64 v134, v[82:83] offset:80
	ds_write_b64 v134, v[84:85] offset:96
	ds_write_b64 v134, v[86:87] offset:112
	ds_write_b64 v134, v[64:65] offset:16960
	ds_write_b64 v134, v[66:67] offset:16976
	ds_write_b64 v134, v[68:69] offset:16992
	ds_write_b64 v134, v[70:71] offset:17008
	ds_write_b64 v134, v[48:49] offset:128
	ds_write_b64 v134, v[50:51] offset:144
	ds_write_b64 v134, v[52:53] offset:160
	ds_write_b64 v134, v[54:55] offset:176
	ds_write_b64 v134, v[32:33] offset:17024
	ds_write_b64 v134, v[34:35] offset:17040
	ds_write_b64 v134, v[36:37] offset:17056
	ds_write_b64 v134, v[38:39] offset:17072
	ds_write_b64 v134, v[16:17] offset:192
	ds_write_b64 v134, v[18:19] offset:208
	ds_write_b64 v134, v[20:21] offset:224
	ds_write_b64 v134, v[22:23] offset:240
	ds_write_b64 v134, v[0:1] offset:17088
	ds_write_b64 v134, v[2:3] offset:17104
	ds_write_b64 v134, v[4:5] offset:17120
	ds_write_b64 v134, v[6:7] offset:17136
	s_waitcnt lgkmcnt(0)
	s_barrier
	v_lshl_add_u32 v136, v129, 5, v131
	v_mul_u32_u24_e32 v137, 528, v136
	v_lshl_add_u32 v137, v130, 4, v137
	v_add_u32_e32 v137, 64, v137
	v_add_u32_e32 v136, s12, v136
	v_lshlrev_b32_e32 v136, 12, v136
	v_lshl_add_u32 v136, v130, 4, v136
	s_lshl_b32 s22, s13, 1
	v_add_u32_e32 v136, s22, v136
	ds_read_b128 v[0:3], v137 offset:0
	ds_read_b128 v[4:7], v137 offset:1056
	ds_read_b128 v[8:11], v137 offset:2112
	ds_read_b128 v[12:15], v137 offset:3168
	ds_read_b128 v[16:19], v137 offset:4224
	ds_read_b128 v[20:23], v137 offset:5280
	ds_read_b128 v[24:27], v137 offset:6336
	ds_read_b128 v[28:31], v137 offset:7392
	ds_read_b128 v[32:35], v137 offset:8448
	ds_read_b128 v[36:39], v137 offset:9504
	ds_read_b128 v[40:43], v137 offset:10560
	ds_read_b128 v[44:47], v137 offset:11616
	ds_read_b128 v[48:51], v137 offset:12672
	ds_read_b128 v[52:55], v137 offset:13728
	ds_read_b128 v[56:59], v137 offset:14784
	ds_read_b128 v[60:63], v137 offset:15840
	s_waitcnt lgkmcnt(15)
	global_store_dwordx4 v136, v[0:3], s[20:21]
	v_add_u32_e32 v136, 0x2000, v136
	s_waitcnt lgkmcnt(14)
	global_store_dwordx4 v136, v[4:7], s[20:21]
	v_add_u32_e32 v136, 0x2000, v136
	s_waitcnt lgkmcnt(13)
	global_store_dwordx4 v136, v[8:11], s[20:21]
	v_add_u32_e32 v136, 0x2000, v136
	s_waitcnt lgkmcnt(12)
	global_store_dwordx4 v136, v[12:15], s[20:21]
	v_add_u32_e32 v136, 0x2000, v136
	s_waitcnt lgkmcnt(11)
	global_store_dwordx4 v136, v[16:19], s[20:21]
	v_add_u32_e32 v136, 0x2000, v136
	s_waitcnt lgkmcnt(10)
	global_store_dwordx4 v136, v[20:23], s[20:21]
	v_add_u32_e32 v136, 0x2000, v136
	s_waitcnt lgkmcnt(9)
	global_store_dwordx4 v136, v[24:27], s[20:21]
	v_add_u32_e32 v136, 0x2000, v136
	s_waitcnt lgkmcnt(8)
	global_store_dwordx4 v136, v[28:31], s[20:21]
	v_add_u32_e32 v136, 0x2000, v136
	s_waitcnt lgkmcnt(7)
	global_store_dwordx4 v136, v[32:35], s[20:21]
	v_add_u32_e32 v136, 0x2000, v136
	s_waitcnt lgkmcnt(6)
	global_store_dwordx4 v136, v[36:39], s[20:21]
	v_add_u32_e32 v136, 0x2000, v136
	s_waitcnt lgkmcnt(5)
	global_store_dwordx4 v136, v[40:43], s[20:21]
	v_add_u32_e32 v136, 0x2000, v136
	s_waitcnt lgkmcnt(4)
	global_store_dwordx4 v136, v[44:47], s[20:21]
	v_add_u32_e32 v136, 0x2000, v136
	s_waitcnt lgkmcnt(3)
	global_store_dwordx4 v136, v[48:51], s[20:21]
	v_add_u32_e32 v136, 0x2000, v136
	s_waitcnt lgkmcnt(2)
	global_store_dwordx4 v136, v[52:55], s[20:21]
	v_add_u32_e32 v136, 0x2000, v136
	s_waitcnt lgkmcnt(1)
	global_store_dwordx4 v136, v[56:59], s[20:21]
	v_add_u32_e32 v136, 0x2000, v136
	s_waitcnt lgkmcnt(0)
	global_store_dwordx4 v136, v[60:63], s[20:21]
	v_add_u32_e32 v136, 0x2000, v136
	s_cmp_lt_u32 s2, 64
	s_cbranch_scc1 .LBB0_978
